# all 6 GEMM k-loops hand-pipelined (double-buffered LDS fragments, DMA right after barrier) + attention bias-load wait deferred to LDS staging write
# speedup vs baseline: 1.0262x; 1.0262x over previous
; DI int opaque_tid() { int t = threadIdx.x; asm volatile("" : "+v"(t)); return t; }
; DI f32x16 zero16() { f32x16 z; for (int i = 0; i < 16; ++i) z[i] = 0.f; return z; }
; #define GEMM_ISSUE(KT, ST) do { const int k1_ = (KT) << 6; unsigned char* d_ = ldst + (ST) * STAGE; \
;         _Pragma("unroll") for (int j_ = 0; j_ < 4; ++j_) dma16(ap + (size_t)(64 * j_) * lda + k1_, d_ + j_ * 8192); \
;         _Pragma("unroll") for (int j_ = 0; j_ < NBW; ++j_) dma16(bp + bro[j_] + k1_, d_ + BOFF + j_ * 8192); } while (0)
; template <int NBW>
; DI void gemm_mainloop(f32x16 (&acc)[2][NBW], const bf16_t* A, size_t lda, int m0, const bf16_t* Bt, size_t ldb, int n0, int K, unsigned char* lds, bool pre = false, bool only_issue = false) {
;     ...
;     const int t = opaque_tid(), w = t >> 6, lane = t & 63, r = lane & 31, hh = lane >> 5, wm = w >> 1, wn = w & 1;
;     const int drow = w * 8 + (lane >> 3);
;     const int lchunk = (lane & 7) ^ ((drow >> 1) & 7);
;     const bf16_t* ap = A + (size_t)(m0 + drow) * lda + lchunk * 8;
;     const bf16_t* bp = Bt + (size_t)n0 * ldb + lchunk * 8;
;     size_t bro[NBW];
; #pragma unroll
;     for (int j = 0; j < NBW; ++j) {
;         const int rho = 64 * j + drow; const int wnh = rho / (32 * NBW), wi = rho % (32 * NBW);
;         bro[j] = (size_t)(wnh * 32 * NBW + NBW * (wi & 31) + (wi >> 5)) * ldb;
;     }
;     unsigned char* ldst = lds + w * 1024 + lane * 16;
;     ...
;     if (!pre) GEMM_ISSUE(0, 0);
;     if (only_issue) return;
;     __syncthreads();
;     const int nk = K >> 6;
;     const int xr = (r >> 1) & 7;
;     int xo[4];
; #pragma unroll
;     for (int s = 0; s < 4; ++s) xo[s] = ((2 * s + hh) ^ xr) << 4;
;     const int aofs = (wm * 64 + r) * 128;
;     const int bofs = BOFF + (wn * 32 * NBW + r) * 128;
; DI void phase_p1(const Params& P, unsigned char* lds) {
;     ...
;         f32x16 acc[2][4];
; #pragma unroll
;         for (int a = 0; a < 2; ++a)
; #pragma unroll
;             for (int b = 0; b < 4; ++b) acc[a][b] = zero16();
.LBB0_145:
	v_lshrrev_b32_e32 v16, 5, v14
	v_lshrrev_b32_e32 v18, 1, v13
	v_and_b32_e32 v15, 31, v13
	v_lshrrev_b32_e32 v17, 6, v13
	v_bfe_u32 v13, v13, 1, 3
	v_bitop3_b32 v19, v16, v18, 7 bitop3:0x78
	v_lshlrev_b32_e32 v143, 4, v19
	v_bitop3_b32 v19, v16, v13, 2 bitop3:0x36
	v_lshlrev_b32_e32 v144, 4, v19
	v_bitop3_b32 v19, v16, v13, 4 bitop3:0x36
	v_bitop3_b32 v13, v16, v13, 6 bitop3:0x36
	s_mov_b32 s1, 0x1ffffc0
	v_lshlrev_b32_e32 v146, 4, v13
	v_and_or_b32 v13, v18, s1, v15
	v_lshlrev_b32_e32 v12, 7, v12
	s_movk_i32 s1, 0x80
	v_and_or_b32 v12, v12, s1, v15
	v_lshrrev_b32_e32 v14, 3, v14
	v_lshlrev_b32_e32 v148, 7, v12
	v_add3_u32 v12, v11, s20, v6
	v_lshlrev_b16_e32 v6, 3, v17
	v_or_b32_e32 v11, v6, v14
	v_sub_u16_e32 v2, v11, v2
	v_and_b32_e32 v2, 31, v2
	v_lshl_add_u32 v6, v2, 2, v7
	v_sub_u16_e32 v2, v11, v3
	v_and_b32_e32 v2, 31, v2
	v_lshl_add_u32 v2, v2, 2, v8
	v_ashrrev_i32_e32 v3, 31, v2
	v_lshlrev_b64 v[2:3], 11, v[2:3]
	v_lshl_add_u64 v[2:3], v[2:3], 0, s[2:3]
	v_lshl_add_u64 v[2:3], v[2:3], 0, v[138:139]
	v_lshl_add_u64 v[134:135], s[10:11], 0, v[2:3]
	v_sub_u16_e32 v2, v11, v4
	v_and_b32_e32 v2, 31, v2
	v_lshl_add_u32 v2, v2, 2, v9
	v_ashrrev_i32_e32 v3, 31, v2
	v_lshlrev_b64 v[2:3], 11, v[2:3]
	v_lshl_add_u64 v[2:3], v[2:3], 0, s[2:3]
	v_lshl_add_u64 v[2:3], v[2:3], 0, v[138:139]
	v_lshl_add_u64 v[136:137], s[10:11], 0, v[2:3]
	v_sub_u16_e32 v2, v11, v5
	v_and_b32_e32 v2, 31, v2
	v_lshl_add_u32 v2, v2, 2, v10
	v_ashrrev_i32_e32 v3, 31, v2
	v_ashrrev_i32_e32 v7, 31, v6
	v_lshlrev_b64 v[2:3], 11, v[2:3]
	v_lshlrev_b32_e32 v147, 7, v13
	v_ashrrev_i32_e32 v13, 31, v12
	v_lshlrev_b64 v[6:7], 11, v[6:7]
	v_lshl_add_u64 v[2:3], v[2:3], 0, s[2:3]
	v_lshlrev_b64 v[12:13], 11, v[12:13]
	v_readlane_b32 s18, v223, 0
	v_lshl_add_u64 v[6:7], v[6:7], 0, s[2:3]
	v_lshl_add_u64 v[2:3], v[2:3], 0, v[138:139]
	v_or_b32_e32 v12, v12, v138
	v_readlane_b32 s19, v223, 1
	v_lshl_add_u64 v[6:7], v[6:7], 0, v[138:139]
	v_lshl_add_u64 v[140:141], s[10:11], 0, v[2:3]
	v_mov_b32_e32 v2, 0
	v_lshlrev_b32_e32 v145, 4, v19
	v_lshl_add_u64 v[130:131], s[18:19], 0, v[12:13]
	v_lshl_add_u64 v[132:133], s[10:11], 0, v[6:7]
	s_mov_b32 s1, 0
	s_mov_b64 s[2:3], 0
	s_mov_b32 s18, 0x10000
	v_mov_b32_e32 v3, v2
	v_mov_b32_e32 v4, v2
	v_mov_b32_e32 v5, v2
	v_mov_b32_e32 v6, v2
	v_mov_b32_e32 v7, v2
	v_mov_b32_e32 v8, v2
	v_mov_b32_e32 v9, v2
	v_mov_b32_e32 v10, v2
	v_mov_b32_e32 v11, v2
	v_mov_b32_e32 v12, v2
	v_mov_b32_e32 v13, v2
	v_mov_b32_e32 v14, v2
	v_mov_b32_e32 v15, v2
	v_mov_b32_e32 v16, v2
	v_mov_b32_e32 v17, v2
	v_mov_b32_e32 v34, v2
	v_mov_b32_e32 v35, v2
	v_mov_b32_e32 v36, v2
	v_mov_b32_e32 v37, v2
	v_mov_b32_e32 v38, v2
	v_mov_b32_e32 v39, v2
	v_mov_b32_e32 v40, v2
	v_mov_b32_e32 v41, v2
	v_mov_b32_e32 v42, v2
	v_mov_b32_e32 v43, v2
	v_mov_b32_e32 v44, v2
	v_mov_b32_e32 v45, v2
	v_mov_b32_e32 v46, v2
	v_mov_b32_e32 v47, v2
	v_mov_b32_e32 v48, v2
	v_mov_b32_e32 v49, v2
	v_mov_b32_e32 v18, v2
	v_mov_b32_e32 v19, v2
	v_mov_b32_e32 v20, v2
	v_mov_b32_e32 v21, v2
	v_mov_b32_e32 v22, v2
	v_mov_b32_e32 v23, v2
	v_mov_b32_e32 v24, v2
	v_mov_b32_e32 v25, v2
	v_mov_b32_e32 v26, v2
	v_mov_b32_e32 v27, v2
	v_mov_b32_e32 v28, v2
	v_mov_b32_e32 v29, v2
	v_mov_b32_e32 v30, v2
	v_mov_b32_e32 v31, v2
	v_mov_b32_e32 v32, v2
	v_mov_b32_e32 v33, v2
	v_mov_b32_e32 v50, v2
	v_mov_b32_e32 v51, v2
	v_mov_b32_e32 v52, v2
	v_mov_b32_e32 v53, v2
	v_mov_b32_e32 v54, v2
	v_mov_b32_e32 v55, v2
	v_mov_b32_e32 v56, v2
	v_mov_b32_e32 v57, v2
	v_mov_b32_e32 v58, v2
	v_mov_b32_e32 v59, v2
	v_mov_b32_e32 v60, v2
	v_mov_b32_e32 v61, v2
	v_mov_b32_e32 v62, v2
	v_mov_b32_e32 v63, v2
	v_mov_b32_e32 v64, v2
	v_mov_b32_e32 v65, v2
	v_mov_b32_e32 v66, v2
	v_mov_b32_e32 v67, v2
	v_mov_b32_e32 v68, v2
	v_mov_b32_e32 v69, v2
	v_mov_b32_e32 v70, v2
	v_mov_b32_e32 v71, v2
	v_mov_b32_e32 v72, v2
	v_mov_b32_e32 v73, v2
	v_mov_b32_e32 v74, v2
	v_mov_b32_e32 v75, v2
	v_mov_b32_e32 v76, v2
	v_mov_b32_e32 v77, v2
	v_mov_b32_e32 v78, v2
	v_mov_b32_e32 v79, v2
	v_mov_b32_e32 v80, v2
	v_mov_b32_e32 v81, v2
	v_mov_b32_e32 v98, v2
	v_mov_b32_e32 v99, v2
	v_mov_b32_e32 v100, v2
	v_mov_b32_e32 v101, v2
	v_mov_b32_e32 v102, v2
	v_mov_b32_e32 v103, v2
	v_mov_b32_e32 v104, v2
	v_mov_b32_e32 v105, v2
	v_mov_b32_e32 v106, v2
	v_mov_b32_e32 v107, v2
	v_mov_b32_e32 v108, v2
	v_mov_b32_e32 v109, v2
	v_mov_b32_e32 v110, v2
	v_mov_b32_e32 v111, v2
	v_mov_b32_e32 v112, v2
	v_mov_b32_e32 v113, v2
	v_mov_b32_e32 v82, v2
	v_mov_b32_e32 v83, v2
	v_mov_b32_e32 v84, v2
	v_mov_b32_e32 v85, v2
	v_mov_b32_e32 v86, v2
	v_mov_b32_e32 v87, v2
	v_mov_b32_e32 v88, v2
	v_mov_b32_e32 v89, v2
	v_mov_b32_e32 v90, v2
	v_mov_b32_e32 v91, v2
	v_mov_b32_e32 v92, v2
	v_mov_b32_e32 v93, v2
	v_mov_b32_e32 v94, v2
	v_mov_b32_e32 v95, v2
	v_mov_b32_e32 v96, v2
	v_mov_b32_e32 v97, v2
	v_mov_b32_e32 v114, v2
	v_mov_b32_e32 v115, v2
	v_mov_b32_e32 v116, v2
	v_mov_b32_e32 v117, v2
	v_mov_b32_e32 v118, v2
	v_mov_b32_e32 v119, v2
	v_mov_b32_e32 v120, v2
	v_mov_b32_e32 v121, v2
	v_mov_b32_e32 v122, v2
	v_mov_b32_e32 v123, v2
	v_mov_b32_e32 v124, v2
	v_mov_b32_e32 v125, v2
	v_mov_b32_e32 v126, v2
	v_mov_b32_e32 v127, v2
	v_mov_b32_e32 v128, v2
	v_mov_b32_e32 v129, v2
	s_waitcnt vmcnt(0) lgkmcnt(0)
	s_barrier
	v_mov_b32_e32 v138, v147
	v_mov_b32_e32 v149, v148
	s_and_b32 s19, s18, 0x10000
	v_add_u32_e32 v250, s19, v142
	v_lshl_add_u64 v[248:249], v[130:131], 0, s[2:3]
	s_nop 0
	v_readfirstlane_b32 s19, v250
	s_mov_b64 s[22:23], 0x1080
	v_lshl_add_u64 v[250:251], v[248:249], 0, s[22:23]
	s_mov_b32 m0, s19
	s_nop 0
	global_load_lds_dwordx4 v[250:251], off
	s_mov_b64 s[22:23], 0x21080
	v_lshl_add_u64 v[250:251], v[248:249], 0, s[22:23]
	s_add_i32 m0, s19, 0x2000
	s_nop 0
	global_load_lds_dwordx4 v[250:251], off
	s_mov_b64 s[22:23], 0x41080
	v_lshl_add_u64 v[250:251], v[248:249], 0, s[22:23]
	s_add_i32 m0, s19, 0x4000
	s_nop 0
	global_load_lds_dwordx4 v[250:251], off
	s_mov_b64 s[22:23], 0x61080
	v_lshl_add_u64 v[250:251], v[248:249], 0, s[22:23]
	s_add_i32 m0, s19, 0x6000
	s_nop 0
	global_load_lds_dwordx4 v[250:251], off
	v_lshl_add_u64 v[250:251], v[132:133], 0, s[2:3]
	s_add_i32 m0, s19, 0x8000
	s_nop 0
	global_load_lds_dwordx4 v[250:251], off
	v_lshl_add_u64 v[250:251], v[134:135], 0, s[2:3]
	s_add_i32 m0, s19, 0xa000
	s_nop 0
	global_load_lds_dwordx4 v[250:251], off
	v_lshl_add_u64 v[250:251], v[136:137], 0, s[2:3]
	s_add_i32 m0, s19, 0xc000
	s_nop 0
	global_load_lds_dwordx4 v[250:251], off
	v_lshl_add_u64 v[250:251], v[140:141], 0, s[2:3]
	s_add_i32 m0, s19, 0xe000
	s_nop 0
	global_load_lds_dwordx4 v[250:251], off
	s_add_u32 s2, s2, 0x80
	s_addc_u32 s3, s3, 0
	s_add_i32 s18, s18, 0x10000
	v_add_u32_e32 v252, v138, v143
	v_add_u32_e32 v253, v149, v143
	ds_read_b128 v[224:227], v252
	ds_read_b128 v[232:235], v253 offset:32768
	ds_read_b128 v[236:239], v253 offset:36864
	ds_read_b128 v[240:243], v253 offset:40960
	ds_read_b128 v[244:247], v253 offset:45056
	ds_read_b128 v[228:231], v252 offset:4096
; #define MFMA(a, b, c) __builtin_amdgcn_mfma_f32_32x32x16_bf16((a), (b), (c), 0, 0, 0)
; #define GEMM_ISSUE(KT, ST) do { const int k1_ = (KT) << 6; unsigned char* d_ = ldst + (ST) * STAGE; \
;         _Pragma("unroll") for (int j_ = 0; j_ < 4; ++j_) dma16(ap + (size_t)(64 * j_) * lda + k1_, d_ + j_ * 8192); \
;         _Pragma("unroll") for (int j_ = 0; j_ < NBW; ++j_) dma16(bp + bro[j_] + k1_, d_ + BOFF + j_ * 8192); } while (0)
; template <int NBW>
; DI void gemm_mainloop(f32x16 (&acc)[2][NBW], const bf16_t* A, size_t lda, int m0, const bf16_t* Bt, size_t ldb, int n0, int K, unsigned char* lds, bool pre = false, bool only_issue = false) {
;     ...
; #pragma unroll 1
;     for (int kt = 0; kt < nk; ++kt) {
;         const unsigned char* st = lds + (kt & 1) * STAGE;
; #pragma unroll
;         for (int s = 0; s < 4; ++s) {
;             if (s == 1 && kt + 1 < nk) GEMM_ISSUE(kt + 1, (kt + 1) & 1);
;             bf16x8 a[2], b[NBW];
; #pragma unroll
;             for (int mb = 0; mb < 2; ++mb) a[mb] = *(const bf16x8*)(st + aofs + mb * 4096 + xo[s]);
; #pragma unroll
;             for (int nb = 0; nb < NBW; ++nb) b[nb] = *(const bf16x8*)(st + bofs + nb * 4096 + xo[s]);
; #pragma unroll
;             for (int mb = 0; mb < 2; ++mb)
; #pragma unroll
;                 for (int nb = 0; nb < NBW; ++nb) acc[mb][nb] = MFMA(a[mb], b[nb], acc[mb][nb]);
;         }
;         __syncthreads();
.Lp1_kloop:
	v_add_u32_e32 v252, v138, v144
	v_add_u32_e32 v253, v149, v144
	ds_read_b128 v[150:153], v252
	ds_read_b128 v[170:173], v253 offset:32768
	ds_read_b128 v[174:177], v253 offset:36864
	ds_read_b128 v[178:181], v253 offset:40960
	ds_read_b128 v[182:185], v253 offset:45056
	ds_read_b128 v[166:169], v252 offset:4096
	s_waitcnt lgkmcnt(6)
	v_mfma_f32_32x32x16_bf16 v[114:129], v[224:227], v[232:235], v[114:129]
	v_mfma_f32_32x32x16_bf16 v[82:97], v[224:227], v[236:239], v[82:97]
	v_mfma_f32_32x32x16_bf16 v[98:113], v[224:227], v[240:243], v[98:113]
	v_mfma_f32_32x32x16_bf16 v[66:81], v[224:227], v[244:247], v[66:81]
	v_mfma_f32_32x32x16_bf16 v[50:65], v[228:231], v[232:235], v[50:65]
	v_mfma_f32_32x32x16_bf16 v[18:33], v[228:231], v[236:239], v[18:33]
	v_mfma_f32_32x32x16_bf16 v[34:49], v[228:231], v[240:243], v[34:49]
	v_mfma_f32_32x32x16_bf16 v[2:17], v[228:231], v[244:247], v[2:17]
	v_add_u32_e32 v252, v138, v145
	v_add_u32_e32 v253, v149, v145
	ds_read_b128 v[224:227], v252
	ds_read_b128 v[232:235], v253 offset:32768
	ds_read_b128 v[236:239], v253 offset:36864
	ds_read_b128 v[240:243], v253 offset:40960
	ds_read_b128 v[244:247], v253 offset:45056
	ds_read_b128 v[228:231], v252 offset:4096
	s_waitcnt lgkmcnt(6)
	v_mfma_f32_32x32x16_bf16 v[114:129], v[150:153], v[170:173], v[114:129]
	v_mfma_f32_32x32x16_bf16 v[82:97], v[150:153], v[174:177], v[82:97]
	v_mfma_f32_32x32x16_bf16 v[98:113], v[150:153], v[178:181], v[98:113]
	v_mfma_f32_32x32x16_bf16 v[66:81], v[150:153], v[182:185], v[66:81]
	v_mfma_f32_32x32x16_bf16 v[50:65], v[166:169], v[170:173], v[50:65]
	v_mfma_f32_32x32x16_bf16 v[18:33], v[166:169], v[174:177], v[18:33]
	v_mfma_f32_32x32x16_bf16 v[34:49], v[166:169], v[178:181], v[34:49]
	v_mfma_f32_32x32x16_bf16 v[2:17], v[166:169], v[182:185], v[2:17]
	v_add_u32_e32 v252, v138, v146
	v_add_u32_e32 v253, v149, v146
	ds_read_b128 v[150:153], v252
	ds_read_b128 v[170:173], v253 offset:32768
	ds_read_b128 v[174:177], v253 offset:36864
	ds_read_b128 v[178:181], v253 offset:40960
	ds_read_b128 v[182:185], v253 offset:45056
	ds_read_b128 v[166:169], v252 offset:4096
	s_waitcnt lgkmcnt(6)
	v_mfma_f32_32x32x16_bf16 v[114:129], v[224:227], v[232:235], v[114:129]
	v_mfma_f32_32x32x16_bf16 v[82:97], v[224:227], v[236:239], v[82:97]
	v_mfma_f32_32x32x16_bf16 v[98:113], v[224:227], v[240:243], v[98:113]
	v_mfma_f32_32x32x16_bf16 v[66:81], v[224:227], v[244:247], v[66:81]
	v_mfma_f32_32x32x16_bf16 v[50:65], v[228:231], v[232:235], v[50:65]
	v_mfma_f32_32x32x16_bf16 v[18:33], v[228:231], v[236:239], v[18:33]
	v_mfma_f32_32x32x16_bf16 v[34:49], v[228:231], v[240:243], v[34:49]
	v_mfma_f32_32x32x16_bf16 v[2:17], v[228:231], v[244:247], v[2:17]
	v_xor_b32_e32 v138, 0x10000, v138
	v_xor_b32_e32 v149, 0x10000, v149
	s_waitcnt vmcnt(0) lgkmcnt(0)
	s_barrier
	s_cmp_eq_u32 s2, 0x800
	s_cbranch_scc1 .Lp1_klast
	v_add_u32_e32 v252, v138, v143
	v_add_u32_e32 v253, v149, v143
	ds_read_b128 v[224:227], v252
	ds_read_b128 v[232:235], v253 offset:32768
	ds_read_b128 v[236:239], v253 offset:36864
	ds_read_b128 v[240:243], v253 offset:40960
	ds_read_b128 v[244:247], v253 offset:45056
	ds_read_b128 v[228:231], v252 offset:4096
	s_cmp_eq_u32 s2, 0x780
	s_cbranch_scc1 .Lp1_knodma
	v_mfma_f32_32x32x16_bf16 v[114:129], v[150:153], v[170:173], v[114:129]
	s_and_b32 s19, s18, 0x10000
	v_add_u32_e32 v250, s19, v142
	v_lshl_add_u64 v[248:249], v[130:131], 0, s[2:3]
	s_nop 0
	v_readfirstlane_b32 s19, v250
	s_mov_b64 s[22:23], 0x1080
	v_lshl_add_u64 v[250:251], v[248:249], 0, s[22:23]
	s_mov_b32 m0, s19
	s_nop 0
	global_load_lds_dwordx4 v[250:251], off
	v_mfma_f32_32x32x16_bf16 v[82:97], v[150:153], v[174:177], v[82:97]
	s_mov_b64 s[22:23], 0x21080
	v_lshl_add_u64 v[250:251], v[248:249], 0, s[22:23]
	s_add_i32 m0, s19, 0x2000
	s_nop 0
	global_load_lds_dwordx4 v[250:251], off
	v_mfma_f32_32x32x16_bf16 v[98:113], v[150:153], v[178:181], v[98:113]
	s_mov_b64 s[22:23], 0x41080
	v_lshl_add_u64 v[250:251], v[248:249], 0, s[22:23]
	s_add_i32 m0, s19, 0x4000
	s_nop 0
	global_load_lds_dwordx4 v[250:251], off
	v_mfma_f32_32x32x16_bf16 v[66:81], v[150:153], v[182:185], v[66:81]
	s_mov_b64 s[22:23], 0x61080
	v_lshl_add_u64 v[250:251], v[248:249], 0, s[22:23]
	s_add_i32 m0, s19, 0x6000
	s_nop 0
	global_load_lds_dwordx4 v[250:251], off
	v_mfma_f32_32x32x16_bf16 v[50:65], v[166:169], v[170:173], v[50:65]
	v_lshl_add_u64 v[250:251], v[132:133], 0, s[2:3]
	s_add_i32 m0, s19, 0x8000
	s_nop 0
	global_load_lds_dwordx4 v[250:251], off
	v_mfma_f32_32x32x16_bf16 v[18:33], v[166:169], v[174:177], v[18:33]
	v_lshl_add_u64 v[250:251], v[134:135], 0, s[2:3]
	s_add_i32 m0, s19, 0xa000
	s_nop 0
	global_load_lds_dwordx4 v[250:251], off
	v_mfma_f32_32x32x16_bf16 v[34:49], v[166:169], v[178:181], v[34:49]
	v_lshl_add_u64 v[250:251], v[136:137], 0, s[2:3]
	s_add_i32 m0, s19, 0xc000
	s_nop 0
	global_load_lds_dwordx4 v[250:251], off
	v_mfma_f32_32x32x16_bf16 v[2:17], v[166:169], v[182:185], v[2:17]
	v_lshl_add_u64 v[250:251], v[140:141], 0, s[2:3]
	s_add_i32 m0, s19, 0xe000
	s_nop 0
	global_load_lds_dwordx4 v[250:251], off
	s_add_u32 s2, s2, 0x80
	s_addc_u32 s3, s3, 0
	s_add_i32 s18, s18, 0x10000
	s_branch .Lp1_kloop
.Lp1_knodma:
	v_mfma_f32_32x32x16_bf16 v[114:129], v[150:153], v[170:173], v[114:129]
	v_mfma_f32_32x32x16_bf16 v[82:97], v[150:153], v[174:177], v[82:97]
	v_mfma_f32_32x32x16_bf16 v[98:113], v[150:153], v[178:181], v[98:113]
	v_mfma_f32_32x32x16_bf16 v[66:81], v[150:153], v[182:185], v[66:81]
	v_mfma_f32_32x32x16_bf16 v[50:65], v[166:169], v[170:173], v[50:65]
	v_mfma_f32_32x32x16_bf16 v[18:33], v[166:169], v[174:177], v[18:33]
	v_mfma_f32_32x32x16_bf16 v[34:49], v[166:169], v[178:181], v[34:49]
	v_mfma_f32_32x32x16_bf16 v[2:17], v[166:169], v[182:185], v[2:17]
	s_add_u32 s2, s2, 0x80
	s_addc_u32 s3, s3, 0
	s_add_i32 s18, s18, 0x10000
	s_branch .Lp1_kloop
.Lp1_klast:
	v_mfma_f32_32x32x16_bf16 v[114:129], v[150:153], v[170:173], v[114:129]
	v_mfma_f32_32x32x16_bf16 v[82:97], v[150:153], v[174:177], v[82:97]
	v_mfma_f32_32x32x16_bf16 v[98:113], v[150:153], v[178:181], v[98:113]
	v_mfma_f32_32x32x16_bf16 v[66:81], v[150:153], v[182:185], v[66:81]
	v_mfma_f32_32x32x16_bf16 v[50:65], v[166:169], v[170:173], v[50:65]
	v_mfma_f32_32x32x16_bf16 v[18:33], v[166:169], v[174:177], v[18:33]
	v_mfma_f32_32x32x16_bf16 v[34:49], v[166:169], v[178:181], v[34:49]
	v_mfma_f32_32x32x16_bf16 v[2:17], v[166:169], v[182:185], v[2:17]
	s_mov_b32 s1, 16
	s_mov_b32 s19, 0x10000
	s_mov_b64 s[22:23], 0x61080

; #define ATT_GLOAD(KT) do { const int kbase_ = (KT) * 64; \
;         kr[0] = *(const u32x4*)(kg + (size_t)kbase_ * 1024); kr[1] = *(const u32x4*)(kg + (size_t)(kbase_ + 32) * 1024); \
;         vr[0] = *(const u32x4*)(vg + kbase_); vr[1] = *(const u32x4*)(vg + (size_t)64 * LP + kbase_); \
;         if (t < 64) br = (NCK[kbase_ + t] + cref) * LOG2E; } while (0)
; DI void attn_prompt_item(const Params& P, unsigned char* lds, int b, int head, int qb, float qkb2) {
;     ...
; #pragma unroll 1
;     ...
;         const int bi = kt % 3;
;         const unsigned char* sb = lds + bi * BUF;
;         {
;             const f32x4 w0 = *(const f32x4*)(WM + ((kt + 1) & 1) * 8), w1 = *(const f32x4*)(WM + ((kt + 1) & 1) * 8 + 4);
;             const float mfloor = fminf(fminf(fminf(w0.x, w0.y), fminf(w0.z, w0.w)), fminf(fminf(w1.x, w1.y), fminf(w1.z, w1.w)));
;             const float blast = *(const float*)(sb + BOFF + 63 * 4);
;             if (blast + qkb2 < mfloor - 32.f) break;
;         }
;         const bool more = kt > 1;
;         if (more) ATT_GLOAD(kt - 1);
.LBB0_1221:
	s_and_b32 s28, s27, 8
	s_xor_b32 s6, s28, 8
	s_lshl_b32 s6, s6, 2
	s_add_i32 s6, s6, 0
	s_add_i32 s6, s6, 0x1b000
	v_mov_b32_e32 v2, s6
	ds_read_b128 v[86:89], v2
	ds_read_b128 v[90:93], v2 offset:16
	s_mul_hi_u32 s6, s24, 0xaaaaaaab
	s_lshr_b32 s30, s6, 1
	s_mul_i32 s6, s30, 0xfffe5000
	s_waitcnt lgkmcnt(1)
	v_max_f32_e32 v2, v87, v87
	v_max_f32_e32 v16, v86, v86
	v_min_f32_e32 v2, v16, v2
	v_max_f32_e32 v16, v89, v89
	v_max_f32_e32 v17, v88, v88
	s_add_i32 s29, s26, s6
	v_min_f32_e32 v17, v17, v16
	v_mov_b32_e32 v16, s29
	ds_read_b32 v16, v16 offset:36092
	s_waitcnt lgkmcnt(1)
	v_max_f32_e32 v86, v93, v93
	v_max_f32_e32 v87, v92, v92
	v_min_f32_e32 v86, v87, v86
	v_min3_f32 v86, v90, v91, v86
	v_min3_f32 v17, v2, v17, v86
	s_waitcnt lgkmcnt(0)
	v_pk_add_f32 v[16:17], v[162:163], v[16:17]
	s_andn2_b64 s[16:17], s[16:17], exec
	s_and_b64 s[18:19], s[0:1], exec
	v_cmp_nlt_f32_e64 s[6:7], v16, v17
	s_or_b64 s[16:17], s[16:17], s[18:19]
	s_and_saveexec_b64 s[18:19], s[6:7]
	s_cbranch_execz .LBB0_1220
	s_cmp_lg_u32 s66, 0
	s_cselect_b64 s[20:21], -1, 0
	s_cmp_eq_u32 s66, 0
	s_cbranch_scc1 .LBB0_1226
	s_lshl_b64 s[22:23], s[66:67], 11
	v_lshl_add_u64 v[16:17], v[170:171], 0, s[22:23]
	s_add_i32 s22, s66, 32
	s_mov_b32 s23, s67
	s_lshl_b64 s[22:23], s[22:23], 11
	v_lshl_add_u64 v[86:87], v[170:171], 0, s[22:23]
	s_lshl_b64 s[22:23], s[66:67], 1
	global_load_dwordx4 v[146:149], v[16:17], off
	global_load_dwordx4 v[150:153], v[86:87], off
	v_lshl_add_u64 v[16:17], v[172:173], 0, s[22:23]
	v_lshl_add_u64 v[86:87], v[174:175], 0, s[22:23]
	global_load_dwordx4 v[154:157], v[16:17], off
	global_load_dwordx4 v[158:161], v[86:87], off
	s_and_saveexec_b64 s[22:23], s[2:3]
	s_cbranch_execz .LBB0_1225
	global_load_dword v224, v[178:179], off

.LBB0_1238:
	s_mul_hi_u32 s20, s25, 0xaaaaaaab
	s_lshr_b32 s20, s20, 1
	s_mul_i32 s20, s20, 0xfffe5000
	s_add_i32 s22, s26, s20
	v_add_u32_e32 v2, s22, v209
	v_add_u32_e32 v16, 0xffff7000, v2
	v_add_u32_e32 v2, 0xffff9200, v2
	s_waitcnt vmcnt(2)
	ds_write_b128 v2, v[150:153]
	v_add_u32_e32 v2, s22, v207
	ds_write_b128 v16, v[146:149]
	v_add_u32_e32 v16, 0xffffb400, v2
	v_add_u32_e32 v2, 0xffffd800, v2
	s_waitcnt vmcnt(1)
	ds_write_b128 v16, v[154:157]
	s_waitcnt vmcnt(0)
	ds_write_b128 v2, v[158:161]
	s_and_saveexec_b64 s[20:21], s[2:3]
	s_cbranch_execz .LBB0_1218
	v_sub_f32_e32 v224, v224, v198
	v_mul_f32_e32 v200, 0x3fb8aa3b, v224
	v_add_u32_e32 v2, s22, v206
	ds_write_b32 v2, v200
	s_branch .LBB0_1218

; DI int opaque_tid() { int t = threadIdx.x; asm volatile("" : "+v"(t)); return t; }
; DI f32x16 zero16() { f32x16 z; for (int i = 0; i < 16; ++i) z[i] = 0.f; return z; }
; #define GEMM_ISSUE(KT, ST) do { const int k1_ = (KT) << 6; unsigned char* d_ = ldst + (ST) * STAGE; \
;         _Pragma("unroll") for (int j_ = 0; j_ < 4; ++j_) dma16(ap + (size_t)(64 * j_) * lda + k1_, d_ + j_ * 8192); \
;         _Pragma("unroll") for (int j_ = 0; j_ < NBW; ++j_) dma16(bp + bro[j_] + k1_, d_ + BOFF + j_ * 8192); } while (0)
; template <int NBW>
; DI void gemm_mainloop(f32x16 (&acc)[2][NBW], const bf16_t* A, size_t lda, int m0, const bf16_t* Bt, size_t ldb, int n0, int K, unsigned char* lds, bool pre = false, bool only_issue = false) {
;     ...
;     const int t = opaque_tid(), w = t >> 6, lane = t & 63, r = lane & 31, hh = lane >> 5, wm = w >> 1, wn = w & 1;
;     const int drow = w * 8 + (lane >> 3);
;     const int lchunk = (lane & 7) ^ ((drow >> 1) & 7);
;     const bf16_t* ap = A + (size_t)(m0 + drow) * lda + lchunk * 8;
;     const bf16_t* bp = Bt + (size_t)n0 * ldb + lchunk * 8;
;     size_t bro[NBW];
; #pragma unroll
;     for (int j = 0; j < NBW; ++j) {
;         const int rho = 64 * j + drow; const int wnh = rho / (32 * NBW), wi = rho % (32 * NBW);
;         bro[j] = (size_t)(wnh * 32 * NBW + NBW * (wi & 31) + (wi >> 5)) * ldb;
;     }
;     unsigned char* ldst = lds + w * 1024 + lane * 16;
;     ...
;     if (!pre) GEMM_ISSUE(0, 0);
;     if (only_issue) return;
;     __syncthreads();
;     const int nk = K >> 6;
;     const int xr = (r >> 1) & 7;
;     int xo[4];
; #pragma unroll
;     for (int s = 0; s < 4; ++s) xo[s] = ((2 * s + hh) ^ xr) << 4;
;     const int aofs = (wm * 64 + r) * 128;
;     const int bofs = BOFF + (wn * 32 * NBW + r) * 128;
; DI void phase_p4(const Params& P, unsigned char* lds) {
;     ...
;         f32x16 a1[2][2], a2[2][2];
; #pragma unroll
;         for (int a = 0; a < 2; ++a)
; #pragma unroll
;             for (int b = 0; b < 2; ++b) { a1[a][b] = zero16(); a2[a][b] = zero16(); }
;         gemm_mainloop<2>(a1, RO, 1024, m0, W1, 1024, n0, 1024, lds, pre);
.LBB0_1398:
	v_and_b32_e32 v10, 31, v4
	v_lshrrev_b32_e32 v12, 6, v4
	v_lshrrev_b32_e32 v13, 1, v4
	v_bfe_u32 v14, v4, 1, 3
	v_lshlrev_b32_e32 v4, 7, v4
	v_and_b32_e32 v62, 0x2f80, v4
	v_add_u32_e32 v4, s65, v8
	v_add3_u32 v4, v4, v5, s78
	v_ashrrev_i32_e32 v5, 31, v4
	v_lshlrev_b64 v[4:5], 11, v[4:5]
	v_readlane_b32 s76, v223, 0
	v_or_b32_e32 v4, v4, v134
	v_readlane_b32 s77, v223, 1
	v_lshrrev_b32_e32 v11, 5, v9
	v_lshrrev_b32_e32 v9, 3, v9
	v_lshl_add_u64 v[50:51], s[76:77], 0, v[4:5]
	v_lshlrev_b16_e32 v4, 3, v12
	v_or_b32_e32 v8, v4, v9
	v_sub_u16_e32 v2, v8, v2
	v_and_b32_e32 v2, 31, v2
	v_lshl_add_u32 v4, v2, 1, v6
	v_sub_u16_e32 v2, v8, v3
	v_and_b32_e32 v2, 31, v2
	v_lshl_add_u32 v2, v2, 1, v7
	v_ashrrev_i32_e32 v3, 31, v2
	v_ashrrev_i32_e32 v5, 31, v4
	v_lshlrev_b64 v[2:3], 11, v[2:3]
	v_bitop3_b32 v15, v11, v13, 7 bitop3:0x78
	v_lshlrev_b64 v[4:5], 11, v[4:5]
	v_lshl_add_u64 v[2:3], v[2:3], 0, s[72:73]
	v_lshlrev_b32_e32 v57, 4, v15
	v_bitop3_b32 v15, v11, v14, 2 bitop3:0x36
	v_lshl_add_u64 v[4:5], v[4:5], 0, s[72:73]
	v_lshl_add_u64 v[2:3], v[2:3], 0, v[134:135]
	v_lshlrev_b32_e32 v58, 4, v15
	v_bitop3_b32 v15, v11, v14, 4 bitop3:0x36
	v_bitop3_b32 v11, v11, v14, 6 bitop3:0x36
	v_and_or_b32 v10, v13, s79, v10
	v_lshl_add_u64 v[4:5], v[4:5], 0, v[134:135]
	v_lshl_add_u64 v[54:55], s[8:9], 0, v[2:3]
	v_mov_b32_e32 v2, 0
	v_lshlrev_b32_e32 v59, 4, v15
	v_lshlrev_b32_e32 v60, 4, v11
	v_lshlrev_b32_e32 v61, 7, v10
	v_lshl_add_u64 v[52:53], s[8:9], 0, v[4:5]
	s_mov_b64 s[76:77], 0
	s_mov_b32 s67, 0x10000
	v_mov_b32_e32 v3, v2
	v_mov_b32_e32 v4, v2
	v_mov_b32_e32 v5, v2
	v_mov_b32_e32 v6, v2
	v_mov_b32_e32 v7, v2
	v_mov_b32_e32 v8, v2
	v_mov_b32_e32 v9, v2
	v_mov_b32_e32 v10, v2
	v_mov_b32_e32 v11, v2
	v_mov_b32_e32 v12, v2
	v_mov_b32_e32 v13, v2
	v_mov_b32_e32 v14, v2
	v_mov_b32_e32 v15, v2
	v_mov_b32_e32 v16, v2
	v_mov_b32_e32 v17, v2
	v_mov_b32_e32 v18, v2
	v_mov_b32_e32 v19, v2
	v_mov_b32_e32 v20, v2
	v_mov_b32_e32 v21, v2
	v_mov_b32_e32 v22, v2
	v_mov_b32_e32 v23, v2
	v_mov_b32_e32 v24, v2
	v_mov_b32_e32 v25, v2
	v_mov_b32_e32 v26, v2
	v_mov_b32_e32 v27, v2
	v_mov_b32_e32 v28, v2
	v_mov_b32_e32 v29, v2
	v_mov_b32_e32 v30, v2
	v_mov_b32_e32 v31, v2
	v_mov_b32_e32 v32, v2
	v_mov_b32_e32 v33, v2
	v_mov_b32_e32 v34, v2
	v_mov_b32_e32 v35, v2
	v_mov_b32_e32 v36, v2
	v_mov_b32_e32 v37, v2
	v_mov_b32_e32 v38, v2
	v_mov_b32_e32 v39, v2
	v_mov_b32_e32 v40, v2
	v_mov_b32_e32 v41, v2
	v_mov_b32_e32 v42, v2
	v_mov_b32_e32 v43, v2
	v_mov_b32_e32 v44, v2
	v_mov_b32_e32 v45, v2
	v_mov_b32_e32 v46, v2
	v_mov_b32_e32 v47, v2
	v_mov_b32_e32 v48, v2
	v_mov_b32_e32 v49, v2
	v_mov_b32_e32 v66, v2
	v_mov_b32_e32 v67, v2
	v_mov_b32_e32 v68, v2
	v_mov_b32_e32 v69, v2
	v_mov_b32_e32 v70, v2
	v_mov_b32_e32 v71, v2
	v_mov_b32_e32 v72, v2
	v_mov_b32_e32 v73, v2
	v_mov_b32_e32 v74, v2
	v_mov_b32_e32 v75, v2
	v_mov_b32_e32 v76, v2
	v_mov_b32_e32 v77, v2
	v_mov_b32_e32 v78, v2
	v_mov_b32_e32 v79, v2
	v_mov_b32_e32 v80, v2
	v_mov_b32_e32 v81, v2
	s_waitcnt vmcnt(0) lgkmcnt(0)
	s_barrier
	v_mov_b32_e32 v63, v61
	v_mov_b32_e32 v64, v62
	s_and_b32 s71, s67, 0x10000
	v_add_u32_e32 v86, s71, v56
	v_lshl_add_u64 v[84:85], v[50:51], 0, s[76:77]
	s_nop 0
	v_readfirstlane_b32 s71, v86
	s_mov_b64 s[86:87], 0xea81080
	v_lshl_add_u64 v[86:87], v[84:85], 0, s[86:87]
	s_mov_b32 m0, s71
	s_nop 0
	global_load_lds_dwordx4 v[86:87], off
	s_mov_b64 s[86:87], 0xeaa1080
	v_lshl_add_u64 v[86:87], v[84:85], 0, s[86:87]
	s_add_i32 m0, s71, 0x2000
	s_nop 0
	global_load_lds_dwordx4 v[86:87], off
	s_mov_b64 s[86:87], 0xeac1080
	v_lshl_add_u64 v[86:87], v[84:85], 0, s[86:87]
	s_add_i32 m0, s71, 0x4000
	s_nop 0
	global_load_lds_dwordx4 v[86:87], off
	s_mov_b64 s[86:87], 0xeae1080
	v_lshl_add_u64 v[86:87], v[84:85], 0, s[86:87]
	s_add_i32 m0, s71, 0x6000
	s_nop 0
	global_load_lds_dwordx4 v[86:87], off
	v_lshl_add_u64 v[86:87], v[52:53], 0, s[76:77]
	s_add_i32 m0, s71, 0x8000
	s_nop 0
	global_load_lds_dwordx4 v[86:87], off
	v_lshl_add_u64 v[86:87], v[54:55], 0, s[76:77]
	s_add_i32 m0, s71, 0xa000
	s_nop 0
	global_load_lds_dwordx4 v[86:87], off
	s_add_u32 s76, s76, 0x80
	s_addc_u32 s77, s77, 0
	s_add_i32 s67, s67, 0x10000
	v_add_u32_e32 v65, v63, v57
	v_add_u32_e32 v88, v64, v57
	ds_read_b128 v[240:243], v65
	ds_read_b128 v[248:251], v88 offset:32768
	ds_read_b128 v[252:255], v88 offset:36864
	ds_read_b128 v[244:247], v65 offset:4096
; #define MFMA(a, b, c) __builtin_amdgcn_mfma_f32_32x32x16_bf16((a), (b), (c), 0, 0, 0)
; #define GEMM_ISSUE(KT, ST) do { const int k1_ = (KT) << 6; unsigned char* d_ = ldst + (ST) * STAGE; \
;         _Pragma("unroll") for (int j_ = 0; j_ < 4; ++j_) dma16(ap + (size_t)(64 * j_) * lda + k1_, d_ + j_ * 8192); \
;         _Pragma("unroll") for (int j_ = 0; j_ < NBW; ++j_) dma16(bp + bro[j_] + k1_, d_ + BOFF + j_ * 8192); } while (0)
; template <int NBW>
; DI void gemm_mainloop(f32x16 (&acc)[2][NBW], const bf16_t* A, size_t lda, int m0, const bf16_t* Bt, size_t ldb, int n0, int K, unsigned char* lds, bool pre = false, bool only_issue = false) {
;     ...
; #pragma unroll 1
;     for (int kt = 0; kt < nk; ++kt) {
;         const unsigned char* st = lds + (kt & 1) * STAGE;
; #pragma unroll
;         for (int s = 0; s < 4; ++s) {
;             if (s == 1 && kt + 1 < nk) GEMM_ISSUE(kt + 1, (kt + 1) & 1);
;             bf16x8 a[2], b[NBW];
; #pragma unroll
;             for (int mb = 0; mb < 2; ++mb) a[mb] = *(const bf16x8*)(st + aofs + mb * 4096 + xo[s]);
; #pragma unroll
;             for (int nb = 0; nb < NBW; ++nb) b[nb] = *(const bf16x8*)(st + bofs + nb * 4096 + xo[s]);
; #pragma unroll
;             for (int mb = 0; mb < 2; ++mb)
; #pragma unroll
;                 for (int nb = 0; nb < NBW; ++nb) acc[mb][nb] = MFMA(a[mb], b[nb], acc[mb][nb]);
;         }
;         __syncthreads();
.Lp4a_kloop:
	v_add_u32_e32 v65, v63, v58
	v_add_u32_e32 v88, v64, v58
	ds_read_b128 v[224:227], v65
	ds_read_b128 v[232:235], v88 offset:32768
	ds_read_b128 v[236:239], v88 offset:36864
	ds_read_b128 v[228:231], v65 offset:4096
	s_waitcnt lgkmcnt(4)
	v_mfma_f32_32x32x16_bf16 v[66:81], v[240:243], v[248:251], v[66:81]
	v_mfma_f32_32x32x16_bf16 v[34:49], v[240:243], v[252:255], v[34:49]
	v_mfma_f32_32x32x16_bf16 v[18:33], v[244:247], v[248:251], v[18:33]
	v_mfma_f32_32x32x16_bf16 v[2:17], v[244:247], v[252:255], v[2:17]
	v_add_u32_e32 v65, v63, v59
	v_add_u32_e32 v88, v64, v59
	ds_read_b128 v[240:243], v65
	ds_read_b128 v[248:251], v88 offset:32768
	ds_read_b128 v[252:255], v88 offset:36864
	ds_read_b128 v[244:247], v65 offset:4096
	s_waitcnt lgkmcnt(4)
	v_mfma_f32_32x32x16_bf16 v[66:81], v[224:227], v[232:235], v[66:81]
	v_mfma_f32_32x32x16_bf16 v[34:49], v[224:227], v[236:239], v[34:49]
	v_mfma_f32_32x32x16_bf16 v[18:33], v[228:231], v[232:235], v[18:33]
	v_mfma_f32_32x32x16_bf16 v[2:17], v[228:231], v[236:239], v[2:17]
	v_add_u32_e32 v65, v63, v60
	v_add_u32_e32 v88, v64, v60
	ds_read_b128 v[224:227], v65
	ds_read_b128 v[232:235], v88 offset:32768
	ds_read_b128 v[236:239], v88 offset:36864
	ds_read_b128 v[228:231], v65 offset:4096
	s_waitcnt lgkmcnt(4)
	v_mfma_f32_32x32x16_bf16 v[66:81], v[240:243], v[248:251], v[66:81]
	v_mfma_f32_32x32x16_bf16 v[34:49], v[240:243], v[252:255], v[34:49]
	v_mfma_f32_32x32x16_bf16 v[18:33], v[244:247], v[248:251], v[18:33]
	v_mfma_f32_32x32x16_bf16 v[2:17], v[244:247], v[252:255], v[2:17]
	v_xor_b32_e32 v63, 0x10000, v63
	v_xor_b32_e32 v64, 0x10000, v64
	s_waitcnt vmcnt(0) lgkmcnt(0)
	s_barrier
	s_cmp_eq_u32 s76, 0x800
	s_cbranch_scc1 .Lp4a_klast
	v_add_u32_e32 v65, v63, v57
	v_add_u32_e32 v88, v64, v57
	ds_read_b128 v[240:243], v65
	ds_read_b128 v[248:251], v88 offset:32768
	ds_read_b128 v[252:255], v88 offset:36864
	ds_read_b128 v[244:247], v65 offset:4096
	s_cmp_eq_u32 s76, 0x780
	s_cbranch_scc1 .Lp4a_knodma
	v_mfma_f32_32x32x16_bf16 v[66:81], v[224:227], v[232:235], v[66:81]
	s_and_b32 s71, s67, 0x10000
	v_add_u32_e32 v86, s71, v56
	v_lshl_add_u64 v[84:85], v[50:51], 0, s[76:77]
	s_nop 0
	v_readfirstlane_b32 s71, v86
	s_mov_b64 s[86:87], 0xea81080
	v_lshl_add_u64 v[86:87], v[84:85], 0, s[86:87]
	s_mov_b32 m0, s71
	s_nop 0
	global_load_lds_dwordx4 v[86:87], off
	v_mfma_f32_32x32x16_bf16 v[34:49], v[224:227], v[236:239], v[34:49]
	s_mov_b64 s[86:87], 0xeaa1080
	v_lshl_add_u64 v[86:87], v[84:85], 0, s[86:87]
	s_add_i32 m0, s71, 0x2000
	s_nop 0
	global_load_lds_dwordx4 v[86:87], off
	s_mov_b64 s[86:87], 0xeac1080
	v_lshl_add_u64 v[86:87], v[84:85], 0, s[86:87]
	s_add_i32 m0, s71, 0x4000
	s_nop 0
	global_load_lds_dwordx4 v[86:87], off
	v_mfma_f32_32x32x16_bf16 v[18:33], v[228:231], v[232:235], v[18:33]
	s_mov_b64 s[86:87], 0xeae1080
	v_lshl_add_u64 v[86:87], v[84:85], 0, s[86:87]
	s_add_i32 m0, s71, 0x6000
	s_nop 0
	global_load_lds_dwordx4 v[86:87], off
	v_mfma_f32_32x32x16_bf16 v[2:17], v[228:231], v[236:239], v[2:17]
	v_lshl_add_u64 v[86:87], v[52:53], 0, s[76:77]
	s_add_i32 m0, s71, 0x8000
	s_nop 0
	global_load_lds_dwordx4 v[86:87], off
	v_lshl_add_u64 v[86:87], v[54:55], 0, s[76:77]
	s_add_i32 m0, s71, 0xa000
	s_nop 0
	global_load_lds_dwordx4 v[86:87], off
	s_add_u32 s76, s76, 0x80
	s_addc_u32 s77, s77, 0
	s_add_i32 s67, s67, 0x10000
	s_branch .Lp4a_kloop
.Lp4a_knodma:
	v_mfma_f32_32x32x16_bf16 v[66:81], v[224:227], v[232:235], v[66:81]
	v_mfma_f32_32x32x16_bf16 v[34:49], v[224:227], v[236:239], v[34:49]
	v_mfma_f32_32x32x16_bf16 v[18:33], v[228:231], v[232:235], v[18:33]
	v_mfma_f32_32x32x16_bf16 v[2:17], v[228:231], v[236:239], v[2:17]
	s_add_u32 s76, s76, 0x80
	s_addc_u32 s77, s77, 0
	s_add_i32 s67, s67, 0x10000
	s_branch .Lp4a_kloop
.Lp4a_klast:
	v_mfma_f32_32x32x16_bf16 v[66:81], v[224:227], v[232:235], v[66:81]
	v_mfma_f32_32x32x16_bf16 v[34:49], v[224:227], v[236:239], v[34:49]
	v_mfma_f32_32x32x16_bf16 v[18:33], v[228:231], v[232:235], v[18:33]
	v_mfma_f32_32x32x16_bf16 v[2:17], v[228:231], v[236:239], v[2:17]
	s_mov_b32 s71, 0x10000
	s_mov_b64 s[86:87], 0xeae1080
.LBB0_1402:
	v_mov_b32_e32 v60, v1
	s_add_u32 s76, s38, s72
	v_ashrrev_i32_e32 v61, 6, v60
	v_lshlrev_b32_e32 v63, 3, v61
	v_bfe_u32 v64, v60, 3, 3
	v_ashrrev_i32_e32 v52, 31, v60
	v_or_b32_e32 v54, v63, v64
	v_lshrrev_b32_e32 v52, 26, v52
	v_add_u32_e32 v52, v54, v52
	v_lshrrev_b32_e32 v53, 6, v52
	v_mul_i32_i24_e32 v53, 64, v53
	v_sub_u32_e32 v53, v54, v53
	v_and_b32_e32 v58, 63, v60
	v_lshrrev_b32_e32 v65, 1, v54
	v_add_u32_e32 v50, s66, v54
	v_and_b32_e32 v52, 0xffffffc0, v52
	v_lshlrev_b32_e32 v55, 1, v53
	v_ashrrev_i32_e32 v53, 5, v53
	v_xor_b32_e32 v56, v65, v60
	v_ashrrev_i32_e32 v51, 31, v50
	v_and_b32_e32 v55, 62, v55
	v_add_u32_e32 v82, v53, v52
	v_add_u32_e32 v54, 64, v54
	v_lshlrev_b32_e32 v59, 10, v61
	v_lshlrev_b32_e32 v58, 4, v58
	v_lshlrev_b64 v[50:51], 11, v[50:51]
	v_add_u32_e32 v52, v82, v55
	v_ashrrev_i32_e32 v55, 31, v54
	v_lshlrev_b32_e32 v56, 4, v56
	v_add3_u32 v141, 0, v59, v58
	v_lshrrev_b32_e32 v55, 26, v55
	v_lshl_add_u64 v[50:51], s[4:5], 0, v[50:51]
	v_and_b32_e32 v134, 0x70, v56
	v_readfirstlane_b32 s67, v141
	v_add_u32_e32 v85, 0x2000, v141
	v_add_u32_e32 v55, v54, v55
	v_lshl_add_u64 v[50:51], v[50:51], 0, v[134:135]
	s_mov_b32 m0, s67
	v_readfirstlane_b32 s67, v85
	v_add_u32_e32 v85, 0x4000, v141
	v_lshrrev_b32_e32 v57, 6, v55
	global_load_lds_dwordx4 v[50:51], off
	v_lshl_add_u64 v[58:59], v[50:51], 0, s[12:13]
	s_mov_b32 m0, s67
	v_readfirstlane_b32 s67, v85
	v_mul_i32_i24_e32 v57, 64, v57
	global_load_lds_dwordx4 v[58:59], off
	v_lshl_add_u64 v[58:59], v[50:51], 0, s[14:15]
	s_mov_b32 m0, s67
; DI int opaque_tid() { int t = threadIdx.x; asm volatile("" : "+v"(t)); return t; }
; DI f32x16 zero16() { f32x16 z; for (int i = 0; i < 16; ++i) z[i] = 0.f; return z; }
; #define GEMM_ISSUE(KT, ST) do { const int k1_ = (KT) << 6; unsigned char* d_ = ldst + (ST) * STAGE; \
;         _Pragma("unroll") for (int j_ = 0; j_ < 4; ++j_) dma16(ap + (size_t)(64 * j_) * lda + k1_, d_ + j_ * 8192); \
;         _Pragma("unroll") for (int j_ = 0; j_ < NBW; ++j_) dma16(bp + bro[j_] + k1_, d_ + BOFF + j_ * 8192); } while (0)
; template <int NBW>
; DI void gemm_mainloop(f32x16 (&acc)[2][NBW], const bf16_t* A, size_t lda, int m0, const bf16_t* Bt, size_t ldb, int n0, int K, unsigned char* lds, bool pre = false, bool only_issue = false) {
;     ...
;     const int t = opaque_tid(), w = t >> 6, lane = t & 63, r = lane & 31, hh = lane >> 5, wm = w >> 1, wn = w & 1;
;     const int drow = w * 8 + (lane >> 3);
;     const int lchunk = (lane & 7) ^ ((drow >> 1) & 7);
;     const bf16_t* ap = A + (size_t)(m0 + drow) * lda + lchunk * 8;
;     const bf16_t* bp = Bt + (size_t)n0 * ldb + lchunk * 8;
;     size_t bro[NBW];
; #pragma unroll
;     for (int j = 0; j < NBW; ++j) {
;         const int rho = 64 * j + drow; const int wnh = rho / (32 * NBW), wi = rho % (32 * NBW);
;         bro[j] = (size_t)(wnh * 32 * NBW + NBW * (wi & 31) + (wi >> 5)) * ldb;
;     }
;     unsigned char* ldst = lds + w * 1024 + lane * 16;
;     ...
;     if (!pre) GEMM_ISSUE(0, 0);
;     if (only_issue) return;
;     __syncthreads();
;     const int nk = K >> 6;
;     const int xr = (r >> 1) & 7;
;     int xo[4];
; #pragma unroll
;     for (int s = 0; s < 4; ++s) xo[s] = ((2 * s + hh) ^ xr) << 4;
;     const int aofs = (wm * 64 + r) * 128;
;     const int bofs = BOFF + (wn * 32 * NBW + r) * 128;
; DI void phase_p4(const Params& P, unsigned char* lds) {
;     ...
;         f32x16 a1[2][2], a2[2][2];
; #pragma unroll
;         for (int a = 0; a < 2; ++a)
; #pragma unroll
;             for (int b = 0; b < 2; ++b) { a1[a][b] = zero16(); a2[a][b] = zero16(); }
;         gemm_mainloop<2>(a1, RO, 1024, m0, W1, 1024, n0, 1024, lds, pre);
;         gemm_mainloop<2>(a2, FO, 1024, m0, W2, 1024, n0, 1024, lds);
	v_sub_u32_e32 v54, v54, v57
	global_load_lds_dwordx4 v[58:59], off
	v_add_u32_e32 v58, 0x6000, v141
	v_and_b32_e32 v55, 0xffffffc0, v55
	v_lshlrev_b32_e32 v57, 1, v54
	v_ashrrev_i32_e32 v54, 5, v54
	v_readfirstlane_b32 s67, v58
	s_addc_u32 s77, s39, s73
	v_ashrrev_i32_e32 v53, 31, v52
	v_and_b32_e32 v57, 62, v57
	v_add_u32_e32 v83, v54, v55
	v_lshl_add_u64 v[50:51], v[50:51], 0, s[16:17]
	s_mov_b32 m0, s67
	v_add_u32_e32 v58, 0x8000, v141
	v_add_u32_e32 v54, v83, v57
	v_lshl_add_u64 v[56:57], s[76:77], 0, v[134:135]
	global_load_lds_dwordx4 v[50:51], off
	v_lshlrev_b64 v[50:51], 11, v[52:53]
	v_readfirstlane_b32 s67, v58
	v_ashrrev_i32_e32 v55, 31, v54
	v_lshl_add_u64 v[50:51], v[56:57], 0, v[50:51]
	s_mov_b32 m0, s67
	v_add_u32_e32 v52, 0xa000, v141
	global_load_lds_dwordx4 v[50:51], off
	v_lshlrev_b64 v[50:51], 11, v[54:55]
	v_readfirstlane_b32 s67, v52
	v_lshl_add_u64 v[50:51], v[56:57], 0, v[50:51]
	s_mov_b32 m0, s67
	v_and_b32_e32 v62, 31, v60
	global_load_lds_dwordx4 v[50:51], off
	v_bfe_u32 v84, v60, 5, 1
	v_lshrrev_b32_e32 v50, 1, v60
	v_bitop3_b32 v52, v84, v50, 7 bitop3:0x78
	v_and_or_b32 v50, v50, s79, v62
	v_bfe_u32 v51, v60, 1, 3
	v_lshlrev_b32_e32 v151, 7, v50
	v_lshlrev_b32_e32 v50, 7, v60
	v_lshlrev_b32_e32 v143, 4, v52
	v_bitop3_b32 v52, v84, v51, 2 bitop3:0x36
	v_and_b32_e32 v153, 0x2f80, v50
	v_add_u32_e32 v50, s65, v64
	v_lshlrev_b32_e32 v145, 4, v52
	v_bitop3_b32 v52, v84, v51, 4 bitop3:0x36
	v_bitop3_b32 v51, v84, v51, 6 bitop3:0x36
	v_add3_u32 v50, v50, v63, s78
	v_lshlrev_b32_e32 v147, 4, v52
	v_lshlrev_b32_e32 v149, 4, v51
	v_ashrrev_i32_e32 v51, 31, v50
	v_bitop3_b32 v52, v65, 7, v60 bitop3:0x48
	v_lshlrev_b64 v[50:51], 11, v[50:51]
	v_lshlrev_b32_e32 v134, 4, v52
	v_readlane_b32 s76, v223, 0
	v_or_b32_e32 v50, v50, v134
	v_readlane_b32 s77, v223, 1
	s_mov_b32 s65, 0x10000
	s_waitcnt vmcnt(0) lgkmcnt(0)
	v_lshl_add_u64 v[168:169], s[76:77], 0, v[50:51]
	v_lshlrev_b16_e32 v50, 3, v61
	v_or_b32_e32 v50, v50, v64
	v_and_b32_e32 v50, 31, v50
	v_lshlrev_b32_e32 v52, 1, v50
	v_add_u32_e32 v50, v82, v52
	v_ashrrev_i32_e32 v51, 31, v50
	v_lshlrev_b64 v[50:51], 11, v[50:51]
	v_lshl_add_u64 v[50:51], v[50:51], 0, s[72:73]
	v_lshl_add_u64 v[50:51], v[50:51], 0, v[134:135]
	v_lshl_add_u64 v[170:171], s[10:11], 0, v[50:51]
	v_add_u32_e32 v50, v83, v52
	v_ashrrev_i32_e32 v51, 31, v50
	v_lshlrev_b64 v[50:51], 11, v[50:51]
	v_lshl_add_u64 v[50:51], v[50:51], 0, s[72:73]
	v_lshl_add_u64 v[50:51], v[50:51], 0, v[134:135]
	v_lshl_add_u64 v[172:173], s[10:11], 0, v[50:51]
	v_mov_b32_e32 v50, 0
	s_mov_b64 s[72:73], 0
	v_mov_b32_e32 v51, v50
	v_mov_b32_e32 v52, v50
	v_mov_b32_e32 v53, v50
	v_mov_b32_e32 v54, v50
	v_mov_b32_e32 v55, v50
	v_mov_b32_e32 v56, v50
	v_mov_b32_e32 v57, v50
	v_mov_b32_e32 v58, v50
	v_mov_b32_e32 v59, v50
	v_mov_b32_e32 v60, v50
	v_mov_b32_e32 v61, v50
	v_mov_b32_e32 v62, v50
	v_mov_b32_e32 v63, v50
	v_mov_b32_e32 v64, v50
	v_mov_b32_e32 v65, v50
	v_mov_b32_e32 v82, v50
	v_mov_b32_e32 v83, v50
	v_mov_b32_e32 v84, v50
	v_mov_b32_e32 v85, v50
	v_mov_b32_e32 v86, v50
	v_mov_b32_e32 v87, v50
	v_mov_b32_e32 v88, v50
	v_mov_b32_e32 v89, v50
	v_mov_b32_e32 v90, v50
	v_mov_b32_e32 v91, v50
	v_mov_b32_e32 v92, v50
	v_mov_b32_e32 v93, v50
	v_mov_b32_e32 v94, v50
	v_mov_b32_e32 v95, v50
	v_mov_b32_e32 v96, v50
	v_mov_b32_e32 v97, v50
	v_mov_b32_e32 v98, v50
	v_mov_b32_e32 v99, v50
	v_mov_b32_e32 v100, v50
	v_mov_b32_e32 v101, v50
	v_mov_b32_e32 v102, v50
	v_mov_b32_e32 v103, v50
	v_mov_b32_e32 v104, v50
	v_mov_b32_e32 v105, v50
	v_mov_b32_e32 v106, v50
	v_mov_b32_e32 v107, v50
	v_mov_b32_e32 v108, v50
	v_mov_b32_e32 v109, v50
	v_mov_b32_e32 v110, v50
	v_mov_b32_e32 v111, v50
	v_mov_b32_e32 v112, v50
	v_mov_b32_e32 v113, v50
	v_mov_b32_e32 v114, v50
	v_mov_b32_e32 v115, v50
	v_mov_b32_e32 v116, v50
	v_mov_b32_e32 v117, v50
	v_mov_b32_e32 v118, v50
	v_mov_b32_e32 v119, v50
	v_mov_b32_e32 v120, v50
	v_mov_b32_e32 v121, v50
	v_mov_b32_e32 v122, v50
	v_mov_b32_e32 v123, v50
	v_mov_b32_e32 v124, v50
	v_mov_b32_e32 v125, v50
	v_mov_b32_e32 v126, v50
	v_mov_b32_e32 v127, v50
	v_mov_b32_e32 v128, v50
	v_mov_b32_e32 v129, v50
	s_barrier
	v_mov_b32_e32 v134, v151
	v_mov_b32_e32 v155, v153
	s_and_b32 s67, s65, 0x10000
	v_add_u32_e32 v176, s67, v141
	v_lshl_add_u64 v[174:175], v[168:169], 0, s[72:73]
	s_nop 0
	v_readfirstlane_b32 s67, v176
	s_mov_b64 s[76:77], 0x12c01080
	v_lshl_add_u64 v[176:177], v[174:175], 0, s[76:77]
	s_mov_b32 m0, s67
	s_nop 0
	global_load_lds_dwordx4 v[176:177], off
	s_mov_b64 s[76:77], 0x12c21080
	v_lshl_add_u64 v[176:177], v[174:175], 0, s[76:77]
	s_add_i32 m0, s67, 0x2000
	s_nop 0
	global_load_lds_dwordx4 v[176:177], off
	s_mov_b64 s[76:77], 0x12c41080
	v_lshl_add_u64 v[176:177], v[174:175], 0, s[76:77]
	s_add_i32 m0, s67, 0x4000
	s_nop 0
	global_load_lds_dwordx4 v[176:177], off
	s_mov_b64 s[76:77], 0x12c61080
	v_lshl_add_u64 v[176:177], v[174:175], 0, s[76:77]
	s_add_i32 m0, s67, 0x6000
	s_nop 0
	global_load_lds_dwordx4 v[176:177], off
	v_lshl_add_u64 v[176:177], v[170:171], 0, s[72:73]
	s_add_i32 m0, s67, 0x8000
	s_nop 0
	global_load_lds_dwordx4 v[176:177], off
	v_lshl_add_u64 v[176:177], v[172:173], 0, s[72:73]
	s_add_i32 m0, s67, 0xa000
	s_nop 0
	global_load_lds_dwordx4 v[176:177], off
	s_add_u32 s72, s72, 0x80
	s_addc_u32 s73, s73, 0
	s_add_i32 s65, s65, 0x10000
	v_add_u32_e32 v157, v134, v143
	v_add_u32_e32 v159, v155, v143
	ds_read_b128 v[240:243], v157
	ds_read_b128 v[248:251], v159 offset:32768
	ds_read_b128 v[252:255], v159 offset:36864
	ds_read_b128 v[244:247], v157 offset:4096
; #define MFMA(a, b, c) __builtin_amdgcn_mfma_f32_32x32x16_bf16((a), (b), (c), 0, 0, 0)
; #define GEMM_ISSUE(KT, ST) do { const int k1_ = (KT) << 6; unsigned char* d_ = ldst + (ST) * STAGE; \
;         _Pragma("unroll") for (int j_ = 0; j_ < 4; ++j_) dma16(ap + (size_t)(64 * j_) * lda + k1_, d_ + j_ * 8192); \
;         _Pragma("unroll") for (int j_ = 0; j_ < NBW; ++j_) dma16(bp + bro[j_] + k1_, d_ + BOFF + j_ * 8192); } while (0)
; template <int NBW>
; DI void gemm_mainloop(f32x16 (&acc)[2][NBW], const bf16_t* A, size_t lda, int m0, const bf16_t* Bt, size_t ldb, int n0, int K, unsigned char* lds, bool pre = false, bool only_issue = false) {
;     ...
; #pragma unroll 1
;     for (int kt = 0; kt < nk; ++kt) {
;         const unsigned char* st = lds + (kt & 1) * STAGE;
; #pragma unroll
;         for (int s = 0; s < 4; ++s) {
;             if (s == 1 && kt + 1 < nk) GEMM_ISSUE(kt + 1, (kt + 1) & 1);
;             bf16x8 a[2], b[NBW];
; #pragma unroll
;             for (int mb = 0; mb < 2; ++mb) a[mb] = *(const bf16x8*)(st + aofs + mb * 4096 + xo[s]);
; #pragma unroll
;             for (int nb = 0; nb < NBW; ++nb) b[nb] = *(const bf16x8*)(st + bofs + nb * 4096 + xo[s]);
; #pragma unroll
;             for (int mb = 0; mb < 2; ++mb)
; #pragma unroll
;                 for (int nb = 0; nb < NBW; ++nb) acc[mb][nb] = MFMA(a[mb], b[nb], acc[mb][nb]);
;         }
;         __syncthreads();
.Lp4b_kloop:
	v_add_u32_e32 v157, v134, v145
	v_add_u32_e32 v159, v155, v145
	ds_read_b128 v[224:227], v157
	ds_read_b128 v[232:235], v159 offset:32768
	ds_read_b128 v[236:239], v159 offset:36864
	ds_read_b128 v[228:231], v157 offset:4096
	s_waitcnt lgkmcnt(4)
	v_mfma_f32_32x32x16_bf16 v[114:129], v[240:243], v[248:251], v[114:129]
	v_mfma_f32_32x32x16_bf16 v[98:113], v[240:243], v[252:255], v[98:113]
	v_mfma_f32_32x32x16_bf16 v[82:97], v[244:247], v[248:251], v[82:97]
	v_mfma_f32_32x32x16_bf16 v[50:65], v[244:247], v[252:255], v[50:65]
	v_add_u32_e32 v157, v134, v147
	v_add_u32_e32 v159, v155, v147
	ds_read_b128 v[240:243], v157
	ds_read_b128 v[248:251], v159 offset:32768
	ds_read_b128 v[252:255], v159 offset:36864
	ds_read_b128 v[244:247], v157 offset:4096
	s_waitcnt lgkmcnt(4)
	v_mfma_f32_32x32x16_bf16 v[114:129], v[224:227], v[232:235], v[114:129]
	v_mfma_f32_32x32x16_bf16 v[98:113], v[224:227], v[236:239], v[98:113]
	v_mfma_f32_32x32x16_bf16 v[82:97], v[228:231], v[232:235], v[82:97]
	v_mfma_f32_32x32x16_bf16 v[50:65], v[228:231], v[236:239], v[50:65]
	v_add_u32_e32 v157, v134, v149
	v_add_u32_e32 v159, v155, v149
	ds_read_b128 v[224:227], v157
	ds_read_b128 v[232:235], v159 offset:32768
	ds_read_b128 v[236:239], v159 offset:36864
	ds_read_b128 v[228:231], v157 offset:4096
	s_waitcnt lgkmcnt(4)
	v_mfma_f32_32x32x16_bf16 v[114:129], v[240:243], v[248:251], v[114:129]
	v_mfma_f32_32x32x16_bf16 v[98:113], v[240:243], v[252:255], v[98:113]
	v_mfma_f32_32x32x16_bf16 v[82:97], v[244:247], v[248:251], v[82:97]
	v_mfma_f32_32x32x16_bf16 v[50:65], v[244:247], v[252:255], v[50:65]
	v_xor_b32_e32 v134, 0x10000, v134
	v_xor_b32_e32 v155, 0x10000, v155
	s_waitcnt vmcnt(0) lgkmcnt(0)
	s_barrier
	s_cmp_eq_u32 s72, 0x800
	s_cbranch_scc1 .Lp4b_klast
	v_add_u32_e32 v157, v134, v143
	v_add_u32_e32 v159, v155, v143
	ds_read_b128 v[240:243], v157
	ds_read_b128 v[248:251], v159 offset:32768
	ds_read_b128 v[252:255], v159 offset:36864
	ds_read_b128 v[244:247], v157 offset:4096
	s_cmp_eq_u32 s72, 0x780
	s_cbranch_scc1 .Lp4b_knodma
	v_mfma_f32_32x32x16_bf16 v[114:129], v[224:227], v[232:235], v[114:129]
	s_and_b32 s67, s65, 0x10000
	v_add_u32_e32 v176, s67, v141
	v_lshl_add_u64 v[174:175], v[168:169], 0, s[72:73]
	s_nop 0
	v_readfirstlane_b32 s67, v176
	s_mov_b64 s[76:77], 0x12c01080
	v_lshl_add_u64 v[176:177], v[174:175], 0, s[76:77]
	s_mov_b32 m0, s67
	s_nop 0
	global_load_lds_dwordx4 v[176:177], off
	v_mfma_f32_32x32x16_bf16 v[98:113], v[224:227], v[236:239], v[98:113]
	s_mov_b64 s[76:77], 0x12c21080
	v_lshl_add_u64 v[176:177], v[174:175], 0, s[76:77]
	s_add_i32 m0, s67, 0x2000
	s_nop 0
	global_load_lds_dwordx4 v[176:177], off
	s_mov_b64 s[76:77], 0x12c41080
	v_lshl_add_u64 v[176:177], v[174:175], 0, s[76:77]
	s_add_i32 m0, s67, 0x4000
	s_nop 0
	global_load_lds_dwordx4 v[176:177], off
	v_mfma_f32_32x32x16_bf16 v[82:97], v[228:231], v[232:235], v[82:97]
	s_mov_b64 s[76:77], 0x12c61080
	v_lshl_add_u64 v[176:177], v[174:175], 0, s[76:77]
	s_add_i32 m0, s67, 0x6000
	s_nop 0
	global_load_lds_dwordx4 v[176:177], off
	v_mfma_f32_32x32x16_bf16 v[50:65], v[228:231], v[236:239], v[50:65]
	v_lshl_add_u64 v[176:177], v[170:171], 0, s[72:73]
	s_add_i32 m0, s67, 0x8000
	s_nop 0
	global_load_lds_dwordx4 v[176:177], off
	v_lshl_add_u64 v[176:177], v[172:173], 0, s[72:73]
	s_add_i32 m0, s67, 0xa000
	s_nop 0
	global_load_lds_dwordx4 v[176:177], off
	s_add_u32 s72, s72, 0x80
	s_addc_u32 s73, s73, 0
	s_add_i32 s65, s65, 0x10000
	s_branch .Lp4b_kloop
.Lp4b_knodma:
	v_mfma_f32_32x32x16_bf16 v[114:129], v[224:227], v[232:235], v[114:129]
	v_mfma_f32_32x32x16_bf16 v[98:113], v[224:227], v[236:239], v[98:113]
	v_mfma_f32_32x32x16_bf16 v[82:97], v[228:231], v[232:235], v[82:97]
	v_mfma_f32_32x32x16_bf16 v[50:65], v[228:231], v[236:239], v[50:65]
	s_add_u32 s72, s72, 0x80
	s_addc_u32 s73, s73, 0
	s_add_i32 s65, s65, 0x10000
	s_branch .Lp4b_kloop
.Lp4b_klast:
	v_mfma_f32_32x32x16_bf16 v[114:129], v[224:227], v[232:235], v[114:129]
	v_mfma_f32_32x32x16_bf16 v[98:113], v[224:227], v[236:239], v[98:113]
	v_mfma_f32_32x32x16_bf16 v[82:97], v[228:231], v[232:235], v[82:97]
	v_mfma_f32_32x32x16_bf16 v[50:65], v[228:231], v[236:239], v[50:65]
	s_mov_b32 s67, 0x10000
	s_mov_b64 s[76:77], 0x12c61080

; DI int opaque_tid() { int t = threadIdx.x; asm volatile("" : "+v"(t)); return t; }
; DI f32x16 zero16() { f32x16 z; for (int i = 0; i < 16; ++i) z[i] = 0.f; return z; }
; #define GEMM_ISSUE(KT, ST) do { const int k1_ = (KT) << 6; unsigned char* d_ = ldst + (ST) * STAGE; \
;         _Pragma("unroll") for (int j_ = 0; j_ < 4; ++j_) dma16(ap + (size_t)(64 * j_) * lda + k1_, d_ + j_ * 8192); \
;         _Pragma("unroll") for (int j_ = 0; j_ < NBW; ++j_) dma16(bp + bro[j_] + k1_, d_ + BOFF + j_ * 8192); } while (0)
; template <int NBW>
; DI void gemm_mainloop(f32x16 (&acc)[2][NBW], const bf16_t* A, size_t lda, int m0, const bf16_t* Bt, size_t ldb, int n0, int K, unsigned char* lds, bool pre = false, bool only_issue = false) {
;     ...
;     const int t = opaque_tid(), w = t >> 6, lane = t & 63, r = lane & 31, hh = lane >> 5, wm = w >> 1, wn = w & 1;
;     const int drow = w * 8 + (lane >> 3);
;     const int lchunk = (lane & 7) ^ ((drow >> 1) & 7);
;     const bf16_t* ap = A + (size_t)(m0 + drow) * lda + lchunk * 8;
;     const bf16_t* bp = Bt + (size_t)n0 * ldb + lchunk * 8;
;     size_t bro[NBW];
; #pragma unroll
;     for (int j = 0; j < NBW; ++j) {
;         const int rho = 64 * j + drow; const int wnh = rho / (32 * NBW), wi = rho % (32 * NBW);
;         bro[j] = (size_t)(wnh * 32 * NBW + NBW * (wi & 31) + (wi >> 5)) * ldb;
;     }
;     unsigned char* ldst = lds + w * 1024 + lane * 16;
;     ...
;     if (!pre) GEMM_ISSUE(0, 0);
;     if (only_issue) return;
;     __syncthreads();
;     const int nk = K >> 6;
;     const int xr = (r >> 1) & 7;
;     int xo[4];
; #pragma unroll
;     for (int s = 0; s < 4; ++s) xo[s] = ((2 * s + hh) ^ xr) << 4;
;     const int aofs = (wm * 64 + r) * 128;
;     const int bofs = BOFF + (wn * 32 * NBW + r) * 128;
; DI void phase_p5(const Params& P, unsigned char* lds) {
;     ...
;         f32x16 acc[2][4];
; #pragma unroll
;         for (int a = 0; a < 2; ++a)
; #pragma unroll
;             for (int b = 0; b < 4; ++b) acc[a][b] = zero16();
;         gemm_mainloop<4>(acc, M, 1024, m0, W, 1024, n0, 1024, lds, pre);
.LBB0_1487:
	v_and_b32_e32 v15, 31, v13
	v_lshlrev_b32_e32 v11, 7, v11
	v_and_or_b32 v11, v11, s36, v15
	v_lshrrev_b32_e32 v17, 6, v13
	s_waitcnt vmcnt(0)
	v_lshlrev_b32_e32 v146, 7, v11
	v_add_u32_e32 v11, s25, v12
	v_lshrrev_b32_e32 v16, 5, v14
	v_lshrrev_b32_e32 v14, 3, v14
	v_add3_u32 v12, v11, v6, s36
	v_lshlrev_b16_e32 v6, 3, v17
	v_or_b32_e32 v11, v6, v14
	v_sub_u16_e32 v2, v11, v2
	v_and_b32_e32 v2, 31, v2
	v_lshl_add_u32 v6, v2, 2, v7
	v_sub_u16_e32 v2, v11, v3
	v_and_b32_e32 v2, 31, v2
	v_lshl_add_u32 v2, v2, 2, v8
	v_ashrrev_i32_e32 v3, 31, v2
	v_lshlrev_b64 v[2:3], 11, v[2:3]
	v_lshl_add_u64 v[2:3], v[2:3], 0, s[22:23]
	v_lshl_add_u64 v[2:3], v[2:3], 0, v[164:165]
	v_lshl_add_u64 v[134:135], s[6:7], 0, v[2:3]
	v_sub_u16_e32 v2, v11, v4
	v_and_b32_e32 v2, 31, v2
	v_lshl_add_u32 v2, v2, 2, v9
	v_ashrrev_i32_e32 v3, 31, v2
	v_lshlrev_b64 v[2:3], 11, v[2:3]
	v_lshl_add_u64 v[2:3], v[2:3], 0, s[22:23]
	v_lshl_add_u64 v[2:3], v[2:3], 0, v[164:165]
	v_lshrrev_b32_e32 v18, 1, v13
	v_lshl_add_u64 v[136:137], s[6:7], 0, v[2:3]
	v_sub_u16_e32 v2, v11, v5
	v_bfe_u32 v13, v13, 1, 3
	v_bitop3_b32 v19, v16, v18, 7 bitop3:0x78
	v_and_b32_e32 v2, 31, v2
	v_lshlrev_b32_e32 v141, 4, v19
	v_bitop3_b32 v19, v16, v13, 2 bitop3:0x36
	v_lshl_add_u32 v2, v2, 2, v10
	v_lshlrev_b32_e32 v142, 4, v19
	v_bitop3_b32 v19, v16, v13, 4 bitop3:0x36
	v_bitop3_b32 v13, v16, v13, 6 bitop3:0x36
	v_ashrrev_i32_e32 v3, 31, v2
	v_lshlrev_b32_e32 v144, 4, v13
	v_and_or_b32 v13, v18, s37, v15
	v_ashrrev_i32_e32 v7, 31, v6
	v_lshlrev_b64 v[2:3], 11, v[2:3]
	v_lshlrev_b32_e32 v145, 7, v13
	v_ashrrev_i32_e32 v13, 31, v12
	v_lshlrev_b64 v[6:7], 11, v[6:7]
	v_lshl_add_u64 v[2:3], v[2:3], 0, s[22:23]
	v_lshlrev_b64 v[12:13], 11, v[12:13]
	v_readlane_b32 s30, v223, 0
	v_lshl_add_u64 v[6:7], v[6:7], 0, s[22:23]
	v_lshl_add_u64 v[2:3], v[2:3], 0, v[164:165]
	v_or_b32_e32 v12, v12, v164
	v_readlane_b32 s31, v223, 1
	v_lshl_add_u64 v[6:7], v[6:7], 0, v[164:165]
	v_lshl_add_u64 v[138:139], s[6:7], 0, v[2:3]
	v_mov_b32_e32 v2, 0
	v_lshlrev_b32_e32 v143, 4, v19
	v_lshl_add_u64 v[130:131], s[30:31], 0, v[12:13]
	v_lshl_add_u64 v[132:133], s[6:7], 0, v[6:7]
	s_mov_b32 s25, 0
	s_mov_b64 s[22:23], 0
	s_mov_b32 s27, 0x10000
	v_mov_b32_e32 v3, v2
	v_mov_b32_e32 v4, v2
	v_mov_b32_e32 v5, v2
	v_mov_b32_e32 v6, v2
	v_mov_b32_e32 v7, v2
	v_mov_b32_e32 v8, v2
	v_mov_b32_e32 v9, v2
	v_mov_b32_e32 v10, v2
	v_mov_b32_e32 v11, v2
	v_mov_b32_e32 v12, v2
	v_mov_b32_e32 v13, v2
	v_mov_b32_e32 v14, v2
	v_mov_b32_e32 v15, v2
	v_mov_b32_e32 v16, v2
	v_mov_b32_e32 v17, v2
	v_mov_b32_e32 v18, v2
	v_mov_b32_e32 v19, v2
	v_mov_b32_e32 v20, v2
	v_mov_b32_e32 v21, v2
	v_mov_b32_e32 v22, v2
	v_mov_b32_e32 v23, v2
	v_mov_b32_e32 v24, v2
	v_mov_b32_e32 v25, v2
	v_mov_b32_e32 v26, v2
	v_mov_b32_e32 v27, v2
	v_mov_b32_e32 v28, v2
	v_mov_b32_e32 v29, v2
	v_mov_b32_e32 v30, v2
	v_mov_b32_e32 v31, v2
	v_mov_b32_e32 v32, v2
	v_mov_b32_e32 v33, v2
	v_mov_b32_e32 v34, v2
	v_mov_b32_e32 v35, v2
	v_mov_b32_e32 v36, v2
	v_mov_b32_e32 v37, v2
	v_mov_b32_e32 v38, v2
	v_mov_b32_e32 v39, v2
	v_mov_b32_e32 v40, v2
	v_mov_b32_e32 v41, v2
	v_mov_b32_e32 v42, v2
	v_mov_b32_e32 v43, v2
	v_mov_b32_e32 v44, v2
	v_mov_b32_e32 v45, v2
	v_mov_b32_e32 v46, v2
	v_mov_b32_e32 v47, v2
	v_mov_b32_e32 v48, v2
	v_mov_b32_e32 v49, v2
	v_mov_b32_e32 v50, v2
	v_mov_b32_e32 v51, v2
	v_mov_b32_e32 v52, v2
	v_mov_b32_e32 v53, v2
	v_mov_b32_e32 v54, v2
	v_mov_b32_e32 v55, v2
	v_mov_b32_e32 v56, v2
	v_mov_b32_e32 v57, v2
	v_mov_b32_e32 v58, v2
	v_mov_b32_e32 v59, v2
	v_mov_b32_e32 v60, v2
	v_mov_b32_e32 v61, v2
	v_mov_b32_e32 v62, v2
	v_mov_b32_e32 v63, v2
	v_mov_b32_e32 v64, v2
	v_mov_b32_e32 v65, v2
	v_mov_b32_e32 v66, v2
	v_mov_b32_e32 v67, v2
	v_mov_b32_e32 v68, v2
	v_mov_b32_e32 v69, v2
	v_mov_b32_e32 v70, v2
	v_mov_b32_e32 v71, v2
	v_mov_b32_e32 v72, v2
	v_mov_b32_e32 v73, v2
	v_mov_b32_e32 v74, v2
	v_mov_b32_e32 v75, v2
	v_mov_b32_e32 v76, v2
	v_mov_b32_e32 v77, v2
	v_mov_b32_e32 v78, v2
	v_mov_b32_e32 v79, v2
	v_mov_b32_e32 v80, v2
	v_mov_b32_e32 v81, v2
	v_mov_b32_e32 v82, v2
	v_mov_b32_e32 v83, v2
	v_mov_b32_e32 v84, v2
	v_mov_b32_e32 v85, v2
	v_mov_b32_e32 v86, v2
	v_mov_b32_e32 v87, v2
	v_mov_b32_e32 v88, v2
	v_mov_b32_e32 v89, v2
	v_mov_b32_e32 v90, v2
	v_mov_b32_e32 v91, v2
	v_mov_b32_e32 v92, v2
	v_mov_b32_e32 v93, v2
	v_mov_b32_e32 v94, v2
	v_mov_b32_e32 v95, v2
	v_mov_b32_e32 v96, v2
	v_mov_b32_e32 v97, v2
	v_mov_b32_e32 v98, v2
	v_mov_b32_e32 v99, v2
	v_mov_b32_e32 v100, v2
	v_mov_b32_e32 v101, v2
	v_mov_b32_e32 v102, v2
	v_mov_b32_e32 v103, v2
	v_mov_b32_e32 v104, v2
	v_mov_b32_e32 v105, v2
	v_mov_b32_e32 v106, v2
	v_mov_b32_e32 v107, v2
	v_mov_b32_e32 v108, v2
	v_mov_b32_e32 v109, v2
	v_mov_b32_e32 v110, v2
	v_mov_b32_e32 v111, v2
	v_mov_b32_e32 v112, v2
	v_mov_b32_e32 v113, v2
	v_mov_b32_e32 v114, v2
	v_mov_b32_e32 v115, v2
	v_mov_b32_e32 v116, v2
	v_mov_b32_e32 v117, v2
	v_mov_b32_e32 v118, v2
	v_mov_b32_e32 v119, v2
	v_mov_b32_e32 v120, v2
	v_mov_b32_e32 v121, v2
	v_mov_b32_e32 v122, v2
	v_mov_b32_e32 v123, v2
	v_mov_b32_e32 v124, v2
	v_mov_b32_e32 v125, v2
	v_mov_b32_e32 v126, v2
	v_mov_b32_e32 v127, v2
	v_mov_b32_e32 v128, v2
	v_mov_b32_e32 v129, v2
	s_waitcnt lgkmcnt(0)
	s_barrier
	v_mov_b32_e32 v147, v145
	v_mov_b32_e32 v148, v146
	s_and_b32 s29, s27, 0x10000
	v_add_u32_e32 v250, s29, v140
	v_lshl_add_u64 v[248:249], v[130:131], 0, s[22:23]
	s_nop 0
	v_readfirstlane_b32 s29, v250
	v_lshl_add_u64 v[250:251], v[248:249], 0, s[14:15]
	s_mov_b32 m0, s29
	s_nop 0
	global_load_lds_dwordx4 v[250:251], off
	v_lshl_add_u64 v[250:251], v[248:249], 0, s[16:17]
	s_add_i32 m0, s29, 0x2000
	s_nop 0
	global_load_lds_dwordx4 v[250:251], off
	v_lshl_add_u64 v[250:251], v[248:249], 0, s[18:19]
	s_add_i32 m0, s29, 0x4000
	s_nop 0
	global_load_lds_dwordx4 v[250:251], off
	v_lshl_add_u64 v[250:251], v[248:249], 0, s[20:21]
	s_add_i32 m0, s29, 0x6000
	s_nop 0
	global_load_lds_dwordx4 v[250:251], off
	v_lshl_add_u64 v[250:251], v[132:133], 0, s[22:23]
	s_add_i32 m0, s29, 0x8000
	s_nop 0
	global_load_lds_dwordx4 v[250:251], off
	v_lshl_add_u64 v[250:251], v[134:135], 0, s[22:23]
	s_add_i32 m0, s29, 0xa000
	s_nop 0
	global_load_lds_dwordx4 v[250:251], off
	v_lshl_add_u64 v[250:251], v[136:137], 0, s[22:23]
	s_add_i32 m0, s29, 0xc000
	s_nop 0
	global_load_lds_dwordx4 v[250:251], off
	v_lshl_add_u64 v[250:251], v[138:139], 0, s[22:23]
	s_add_i32 m0, s29, 0xe000
	s_nop 0
	global_load_lds_dwordx4 v[250:251], off
	s_add_u32 s22, s22, 0x80
	s_addc_u32 s23, s23, 0
	s_add_i32 s27, s27, 0x10000
	v_add_u32_e32 v252, v147, v141
	v_add_u32_e32 v253, v148, v141
	ds_read_b128 v[224:227], v252
	ds_read_b128 v[232:235], v253 offset:32768
	ds_read_b128 v[236:239], v253 offset:36864
	ds_read_b128 v[240:243], v253 offset:40960
	ds_read_b128 v[244:247], v253 offset:45056
	ds_read_b128 v[228:231], v252 offset:4096
; #define MFMA(a, b, c) __builtin_amdgcn_mfma_f32_32x32x16_bf16((a), (b), (c), 0, 0, 0)
; #define GEMM_ISSUE(KT, ST) do { const int k1_ = (KT) << 6; unsigned char* d_ = ldst + (ST) * STAGE; \
;         _Pragma("unroll") for (int j_ = 0; j_ < 4; ++j_) dma16(ap + (size_t)(64 * j_) * lda + k1_, d_ + j_ * 8192); \
;         _Pragma("unroll") for (int j_ = 0; j_ < NBW; ++j_) dma16(bp + bro[j_] + k1_, d_ + BOFF + j_ * 8192); } while (0)
; template <int NBW>
; DI void gemm_mainloop(f32x16 (&acc)[2][NBW], const bf16_t* A, size_t lda, int m0, const bf16_t* Bt, size_t ldb, int n0, int K, unsigned char* lds, bool pre = false, bool only_issue = false) {
;     ...
; #pragma unroll 1
;     for (int kt = 0; kt < nk; ++kt) {
;         const unsigned char* st = lds + (kt & 1) * STAGE;
; #pragma unroll
;         for (int s = 0; s < 4; ++s) {
;             if (s == 1 && kt + 1 < nk) GEMM_ISSUE(kt + 1, (kt + 1) & 1);
;             bf16x8 a[2], b[NBW];
; #pragma unroll
;             for (int mb = 0; mb < 2; ++mb) a[mb] = *(const bf16x8*)(st + aofs + mb * 4096 + xo[s]);
; #pragma unroll
;             for (int nb = 0; nb < NBW; ++nb) b[nb] = *(const bf16x8*)(st + bofs + nb * 4096 + xo[s]);
; #pragma unroll
;             for (int mb = 0; mb < 2; ++mb)
; #pragma unroll
;                 for (int nb = 0; nb < NBW; ++nb) acc[mb][nb] = MFMA(a[mb], b[nb], acc[mb][nb]);
;         }
;         __syncthreads();
.Lp5_kloop:
	v_add_u32_e32 v252, v147, v142
	v_add_u32_e32 v253, v148, v142
	ds_read_b128 v[150:153], v252
	ds_read_b128 v[158:161], v253 offset:32768
	ds_read_b128 v[170:173], v253 offset:36864
	ds_read_b128 v[174:177], v253 offset:40960
	ds_read_b128 v[178:181], v253 offset:45056
	ds_read_b128 v[154:157], v252 offset:4096
	s_waitcnt lgkmcnt(6)
	v_mfma_f32_32x32x16_bf16 v[114:129], v[224:227], v[232:235], v[114:129]
	v_mfma_f32_32x32x16_bf16 v[98:113], v[224:227], v[236:239], v[98:113]
	v_mfma_f32_32x32x16_bf16 v[82:97], v[224:227], v[240:243], v[82:97]
	v_mfma_f32_32x32x16_bf16 v[66:81], v[224:227], v[244:247], v[66:81]
	v_mfma_f32_32x32x16_bf16 v[50:65], v[228:231], v[232:235], v[50:65]
	v_mfma_f32_32x32x16_bf16 v[34:49], v[228:231], v[236:239], v[34:49]
	v_mfma_f32_32x32x16_bf16 v[18:33], v[228:231], v[240:243], v[18:33]
	v_mfma_f32_32x32x16_bf16 v[2:17], v[228:231], v[244:247], v[2:17]
	v_add_u32_e32 v252, v147, v143
	v_add_u32_e32 v253, v148, v143
	ds_read_b128 v[224:227], v252
	ds_read_b128 v[232:235], v253 offset:32768
	ds_read_b128 v[236:239], v253 offset:36864
	ds_read_b128 v[240:243], v253 offset:40960
	ds_read_b128 v[244:247], v253 offset:45056
	ds_read_b128 v[228:231], v252 offset:4096
	s_waitcnt lgkmcnt(6)
	v_mfma_f32_32x32x16_bf16 v[114:129], v[150:153], v[158:161], v[114:129]
	v_mfma_f32_32x32x16_bf16 v[98:113], v[150:153], v[170:173], v[98:113]
	v_mfma_f32_32x32x16_bf16 v[82:97], v[150:153], v[174:177], v[82:97]
	v_mfma_f32_32x32x16_bf16 v[66:81], v[150:153], v[178:181], v[66:81]
	v_mfma_f32_32x32x16_bf16 v[50:65], v[154:157], v[158:161], v[50:65]
	v_mfma_f32_32x32x16_bf16 v[34:49], v[154:157], v[170:173], v[34:49]
	v_mfma_f32_32x32x16_bf16 v[18:33], v[154:157], v[174:177], v[18:33]
	v_mfma_f32_32x32x16_bf16 v[2:17], v[154:157], v[178:181], v[2:17]
	v_add_u32_e32 v252, v147, v144
	v_add_u32_e32 v253, v148, v144
	ds_read_b128 v[150:153], v252
	ds_read_b128 v[158:161], v253 offset:32768
	ds_read_b128 v[170:173], v253 offset:36864
	ds_read_b128 v[174:177], v253 offset:40960
	ds_read_b128 v[178:181], v253 offset:45056
	ds_read_b128 v[154:157], v252 offset:4096
	s_waitcnt lgkmcnt(6)
	v_mfma_f32_32x32x16_bf16 v[114:129], v[224:227], v[232:235], v[114:129]
	v_mfma_f32_32x32x16_bf16 v[98:113], v[224:227], v[236:239], v[98:113]
	v_mfma_f32_32x32x16_bf16 v[82:97], v[224:227], v[240:243], v[82:97]
	v_mfma_f32_32x32x16_bf16 v[66:81], v[224:227], v[244:247], v[66:81]
	v_mfma_f32_32x32x16_bf16 v[50:65], v[228:231], v[232:235], v[50:65]
	v_mfma_f32_32x32x16_bf16 v[34:49], v[228:231], v[236:239], v[34:49]
	v_mfma_f32_32x32x16_bf16 v[18:33], v[228:231], v[240:243], v[18:33]
	v_mfma_f32_32x32x16_bf16 v[2:17], v[228:231], v[244:247], v[2:17]
	v_xor_b32_e32 v147, 0x10000, v147
	v_xor_b32_e32 v148, 0x10000, v148
	s_waitcnt vmcnt(0) lgkmcnt(0)
	s_barrier
	s_cmp_eq_u32 s22, 0x800
	s_cbranch_scc1 .Lp5_klast
	v_add_u32_e32 v252, v147, v141
	v_add_u32_e32 v253, v148, v141
	ds_read_b128 v[224:227], v252
	ds_read_b128 v[232:235], v253 offset:32768
	ds_read_b128 v[236:239], v253 offset:36864
	ds_read_b128 v[240:243], v253 offset:40960
	ds_read_b128 v[244:247], v253 offset:45056
	ds_read_b128 v[228:231], v252 offset:4096
	s_cmp_eq_u32 s22, 0x780
	s_cbranch_scc1 .Lp5_knodma
	v_mfma_f32_32x32x16_bf16 v[114:129], v[150:153], v[158:161], v[114:129]
	s_and_b32 s29, s27, 0x10000
	v_add_u32_e32 v250, s29, v140
	v_lshl_add_u64 v[248:249], v[130:131], 0, s[22:23]
	s_nop 0
	v_readfirstlane_b32 s29, v250
	v_lshl_add_u64 v[250:251], v[248:249], 0, s[14:15]
	s_mov_b32 m0, s29
	s_nop 0
	global_load_lds_dwordx4 v[250:251], off
	v_mfma_f32_32x32x16_bf16 v[98:113], v[150:153], v[170:173], v[98:113]
	v_lshl_add_u64 v[250:251], v[248:249], 0, s[16:17]
	s_add_i32 m0, s29, 0x2000
	s_nop 0
	global_load_lds_dwordx4 v[250:251], off
	v_mfma_f32_32x32x16_bf16 v[82:97], v[150:153], v[174:177], v[82:97]
	v_lshl_add_u64 v[250:251], v[248:249], 0, s[18:19]
	s_add_i32 m0, s29, 0x4000
	s_nop 0
	global_load_lds_dwordx4 v[250:251], off
	v_mfma_f32_32x32x16_bf16 v[66:81], v[150:153], v[178:181], v[66:81]
	v_lshl_add_u64 v[250:251], v[248:249], 0, s[20:21]
	s_add_i32 m0, s29, 0x6000
	s_nop 0
	global_load_lds_dwordx4 v[250:251], off
	v_mfma_f32_32x32x16_bf16 v[50:65], v[154:157], v[158:161], v[50:65]
	v_lshl_add_u64 v[250:251], v[132:133], 0, s[22:23]
	s_add_i32 m0, s29, 0x8000
	s_nop 0
	global_load_lds_dwordx4 v[250:251], off
	v_mfma_f32_32x32x16_bf16 v[34:49], v[154:157], v[170:173], v[34:49]
	v_lshl_add_u64 v[250:251], v[134:135], 0, s[22:23]
	s_add_i32 m0, s29, 0xa000
	s_nop 0
	global_load_lds_dwordx4 v[250:251], off
	v_mfma_f32_32x32x16_bf16 v[18:33], v[154:157], v[174:177], v[18:33]
	v_lshl_add_u64 v[250:251], v[136:137], 0, s[22:23]
	s_add_i32 m0, s29, 0xc000
	s_nop 0
	global_load_lds_dwordx4 v[250:251], off
	v_mfma_f32_32x32x16_bf16 v[2:17], v[154:157], v[178:181], v[2:17]
	v_lshl_add_u64 v[250:251], v[138:139], 0, s[22:23]
	s_add_i32 m0, s29, 0xe000
	s_nop 0
	global_load_lds_dwordx4 v[250:251], off
	s_add_u32 s22, s22, 0x80
	s_addc_u32 s23, s23, 0
	s_add_i32 s27, s27, 0x10000
	s_branch .Lp5_kloop
.Lp5_knodma:
	v_mfma_f32_32x32x16_bf16 v[114:129], v[150:153], v[158:161], v[114:129]
	v_mfma_f32_32x32x16_bf16 v[98:113], v[150:153], v[170:173], v[98:113]
	v_mfma_f32_32x32x16_bf16 v[82:97], v[150:153], v[174:177], v[82:97]
	v_mfma_f32_32x32x16_bf16 v[66:81], v[150:153], v[178:181], v[66:81]
	v_mfma_f32_32x32x16_bf16 v[50:65], v[154:157], v[158:161], v[50:65]
	v_mfma_f32_32x32x16_bf16 v[34:49], v[154:157], v[170:173], v[34:49]
	v_mfma_f32_32x32x16_bf16 v[18:33], v[154:157], v[174:177], v[18:33]
	v_mfma_f32_32x32x16_bf16 v[2:17], v[154:157], v[178:181], v[2:17]
	s_add_u32 s22, s22, 0x80
	s_addc_u32 s23, s23, 0
	s_add_i32 s27, s27, 0x10000
	s_branch .Lp5_kloop
.Lp5_klast:
	v_mfma_f32_32x32x16_bf16 v[114:129], v[150:153], v[158:161], v[114:129]
	v_mfma_f32_32x32x16_bf16 v[98:113], v[150:153], v[170:173], v[98:113]
	v_mfma_f32_32x32x16_bf16 v[82:97], v[150:153], v[174:177], v[82:97]
	v_mfma_f32_32x32x16_bf16 v[66:81], v[150:153], v[178:181], v[66:81]
	v_mfma_f32_32x32x16_bf16 v[50:65], v[154:157], v[158:161], v[50:65]
	v_mfma_f32_32x32x16_bf16 v[34:49], v[154:157], v[170:173], v[34:49]
	v_mfma_f32_32x32x16_bf16 v[18:33], v[154:157], v[174:177], v[18:33]
	v_mfma_f32_32x32x16_bf16 v[2:17], v[154:157], v[178:181], v[2:17]
	s_mov_b32 s25, 16
	s_mov_b32 s29, 0x10000

; DI float frsq(float x) { return __builtin_amdgcn_rsqf(x); }
; DI int opaque_tid() { int t = threadIdx.x; asm volatile("" : "+v"(t)); return t; }
; DI f32x16 zero16() { f32x16 z; for (int i = 0; i < 16; ++i) z[i] = 0.f; return z; }
; template <int NBW>
; DI void gemm_mainloop(f32x16 (&acc)[2][NBW], const bf16_t* A, size_t lda, int m0, const bf16_t* Bt, size_t ldb, int n0, int K, unsigned char* lds, bool pre = false, bool only_issue = false) {
;     ...
;     const int t = opaque_tid(), w = t >> 6, lane = t & 63, r = lane & 31, hh = lane >> 5, wm = w >> 1, wn = w & 1;
;     const int drow = w * 8 + (lane >> 3);
;     const int lchunk = (lane & 7) ^ ((drow >> 1) & 7);
;     const bf16_t* ap = A + (size_t)(m0 + drow) * lda + lchunk * 8;
;     const bf16_t* bp = Bt + (size_t)n0 * ldb + lchunk * 8;
;     size_t bro[NBW];
; #pragma unroll
;     for (int j = 0; j < NBW; ++j) {
;         const int rho = 64 * j + drow; const int wnh = rho / (32 * NBW), wi = rho % (32 * NBW);
;         bro[j] = (size_t)(wnh * 32 * NBW + NBW * (wi & 31) + (wi >> 5)) * ldb;
;     }
;     unsigned char* ldst = lds + w * 1024 + lane * 16;
;     ...
;     if (!pre) GEMM_ISSUE(0, 0);
;     if (only_issue) return;
;     __syncthreads();
;     const int nk = K >> 6;
;     const int xr = (r >> 1) & 7;
;     int xo[4];
; #pragma unroll
;     for (int s = 0; s < 4; ++s) xo[s] = ((2 * s + hh) ^ xr) << 4;
;     const int aofs = (wm * 64 + r) * 128;
;     const int bofs = BOFF + (wn * 32 * NBW + r) * 128;
; DI void phase_p6(const Params& P, unsigned char* lds) {
;     ...
;         f32x16 acc[2][4];
; #pragma unroll
;         for (int a = 0; a < 2; ++a)
; #pragma unroll
;             for (int b = 0; b < 4; ++b) acc[a][b] = zero16();
;         {
;             float* rt = (float*)(lds + 131072 + (rtpar & 1) * 1024);
;             if (t < 256) {
;                 const size_t row = (size_t)m0 + t;
;                 const f32x4 s0 = *(const f32x4*)(SSQ + row * 8), s1 = *(const f32x4*)(SSQ + row * 8 + 4);
;                 const float ss = ((s0.x + s0.y) + (s0.z + s0.w)) + ((s1.x + s1.y) + (s1.z + s1.w));
;                 rt[t] = frsq(ss * (1.f / 1024.f) + EPS);
;             }
;         }
;         gemm_mainloop<4>(acc, A2, 1024, m0, W, 1024, n0, 1024, lds, pre);
.LBB0_1638:
	v_lshrrev_b32_e32 v16, 5, v14
	v_lshrrev_b32_e32 v17, 3, v14
	v_lshrrev_b32_e32 v14, 1, v13
	v_and_b32_e32 v15, 31, v13
	v_lshrrev_b32_e32 v18, 6, v13
	v_bfe_u32 v13, v13, 1, 3
	v_bitop3_b32 v19, v16, v14, 7 bitop3:0x78
	v_lshlrev_b32_e32 v7, 7, v7
	v_lshlrev_b32_e32 v165, 4, v19
	v_bitop3_b32 v19, v16, v13, 2 bitop3:0x36
	v_and_or_b32 v7, v7, s36, v15
	v_lshlrev_b32_e32 v166, 4, v19
	v_bitop3_b32 v19, v16, v13, 4 bitop3:0x36
	v_bitop3_b32 v13, v16, v13, 6 bitop3:0x36
	v_lshlrev_b32_e32 v170, 7, v7
	v_add_u32_e32 v7, s41, v8
	v_lshlrev_b32_e32 v168, 4, v13
	v_and_or_b32 v13, v14, s38, v15
	v_add3_u32 v14, v7, v2, s36
	v_lshlrev_b16_e32 v2, 3, v18
	v_or_b32_e32 v7, v2, v17
	v_sub_u16_e32 v2, v7, v3
	v_and_b32_e32 v2, 31, v2
	v_lshl_add_u32 v2, v2, 2, v9
	v_ashrrev_i32_e32 v3, 31, v2
	v_lshlrev_b64 v[2:3], 11, v[2:3]
	v_lshl_add_u64 v[2:3], v[2:3], 0, s[28:29]
	v_lshl_add_u64 v[2:3], v[2:3], 0, v[132:133]
	v_lshl_add_u64 v[136:137], s[8:9], 0, v[2:3]
	v_sub_u16_e32 v2, v7, v4
	v_and_b32_e32 v2, 31, v2
	v_lshl_add_u32 v2, v2, 2, v10
	v_ashrrev_i32_e32 v3, 31, v2
	v_lshlrev_b64 v[2:3], 11, v[2:3]
	v_lshl_add_u64 v[2:3], v[2:3], 0, s[28:29]
	v_lshl_add_u64 v[2:3], v[2:3], 0, v[132:133]
	v_lshl_add_u64 v[138:139], s[8:9], 0, v[2:3]
	v_sub_u16_e32 v2, v7, v5
	v_and_b32_e32 v2, 31, v2
	v_lshl_add_u32 v2, v2, 2, v11
	v_ashrrev_i32_e32 v3, 31, v2
	v_lshlrev_b64 v[2:3], 11, v[2:3]
	v_lshl_add_u64 v[2:3], v[2:3], 0, s[28:29]
	v_lshl_add_u64 v[2:3], v[2:3], 0, v[132:133]
	v_lshl_add_u64 v[140:141], s[8:9], 0, v[2:3]
	v_sub_u16_e32 v2, v7, v6
	v_and_b32_e32 v2, 31, v2
	v_lshl_add_u32 v2, v2, 2, v12
	v_ashrrev_i32_e32 v3, 31, v2
	v_lshlrev_b64 v[2:3], 11, v[2:3]
	v_ashrrev_i32_e32 v15, 31, v14
	v_lshl_add_u64 v[2:3], v[2:3], 0, s[28:29]
	v_lshlrev_b64 v[14:15], 11, v[14:15]
	v_lshl_add_u64 v[2:3], v[2:3], 0, v[132:133]
	v_or_b32_e32 v14, v14, v132
	v_lshl_add_u64 v[142:143], s[8:9], 0, v[2:3]
	v_mov_b32_e32 v2, 0
	v_lshlrev_b32_e32 v167, 4, v19
	v_lshlrev_b32_e32 v169, 7, v13
	v_lshl_add_u64 v[134:135], s[50:51], 0, v[14:15]
	s_mov_b32 s25, 0
	s_mov_b64 s[28:29], 0
	s_mov_b32 s27, 0x10000
	v_mov_b32_e32 v3, v2
	v_mov_b32_e32 v4, v2
	v_mov_b32_e32 v5, v2
	v_mov_b32_e32 v6, v2
	v_mov_b32_e32 v7, v2
	v_mov_b32_e32 v8, v2
	v_mov_b32_e32 v9, v2
	v_mov_b32_e32 v10, v2
	v_mov_b32_e32 v11, v2
	v_mov_b32_e32 v12, v2
	v_mov_b32_e32 v13, v2
	v_mov_b32_e32 v14, v2
	v_mov_b32_e32 v15, v2
	v_mov_b32_e32 v16, v2
	v_mov_b32_e32 v17, v2
	v_mov_b32_e32 v18, v2
	v_mov_b32_e32 v19, v2
	v_mov_b32_e32 v20, v2
	v_mov_b32_e32 v21, v2
	v_mov_b32_e32 v22, v2
	v_mov_b32_e32 v23, v2
	v_mov_b32_e32 v24, v2
	v_mov_b32_e32 v25, v2
	v_mov_b32_e32 v26, v2
	v_mov_b32_e32 v27, v2
	v_mov_b32_e32 v28, v2
	v_mov_b32_e32 v29, v2
	v_mov_b32_e32 v30, v2
	v_mov_b32_e32 v31, v2
	v_mov_b32_e32 v32, v2
	v_mov_b32_e32 v33, v2
	v_mov_b32_e32 v34, v2
	v_mov_b32_e32 v35, v2
	v_mov_b32_e32 v36, v2
	v_mov_b32_e32 v37, v2
	v_mov_b32_e32 v38, v2
	v_mov_b32_e32 v39, v2
	v_mov_b32_e32 v40, v2
	v_mov_b32_e32 v41, v2
	v_mov_b32_e32 v42, v2
	v_mov_b32_e32 v43, v2
	v_mov_b32_e32 v44, v2
	v_mov_b32_e32 v45, v2
	v_mov_b32_e32 v46, v2
	v_mov_b32_e32 v47, v2
	v_mov_b32_e32 v48, v2
	v_mov_b32_e32 v49, v2
	v_mov_b32_e32 v50, v2
	v_mov_b32_e32 v51, v2
	v_mov_b32_e32 v52, v2
	v_mov_b32_e32 v53, v2
	v_mov_b32_e32 v54, v2
	v_mov_b32_e32 v55, v2
	v_mov_b32_e32 v56, v2
	v_mov_b32_e32 v57, v2
	v_mov_b32_e32 v58, v2
	v_mov_b32_e32 v59, v2
	v_mov_b32_e32 v60, v2
	v_mov_b32_e32 v61, v2
	v_mov_b32_e32 v62, v2
	v_mov_b32_e32 v63, v2
	v_mov_b32_e32 v64, v2
	v_mov_b32_e32 v65, v2
	v_mov_b32_e32 v66, v2
	v_mov_b32_e32 v67, v2
	v_mov_b32_e32 v68, v2
	v_mov_b32_e32 v69, v2
	v_mov_b32_e32 v70, v2
	v_mov_b32_e32 v71, v2
	v_mov_b32_e32 v72, v2
	v_mov_b32_e32 v73, v2
	v_mov_b32_e32 v74, v2
	v_mov_b32_e32 v75, v2
	v_mov_b32_e32 v76, v2
	v_mov_b32_e32 v77, v2
	v_mov_b32_e32 v78, v2
	v_mov_b32_e32 v79, v2
	v_mov_b32_e32 v80, v2
	v_mov_b32_e32 v81, v2
	v_mov_b32_e32 v82, v2
	v_mov_b32_e32 v83, v2
	v_mov_b32_e32 v84, v2
	v_mov_b32_e32 v85, v2
	v_mov_b32_e32 v86, v2
	v_mov_b32_e32 v87, v2
	v_mov_b32_e32 v88, v2
	v_mov_b32_e32 v89, v2
	v_mov_b32_e32 v90, v2
	v_mov_b32_e32 v91, v2
	v_mov_b32_e32 v92, v2
	v_mov_b32_e32 v93, v2
	v_mov_b32_e32 v94, v2
	v_mov_b32_e32 v95, v2
	v_mov_b32_e32 v96, v2
	v_mov_b32_e32 v97, v2
	v_mov_b32_e32 v98, v2
	v_mov_b32_e32 v99, v2
	v_mov_b32_e32 v100, v2
	v_mov_b32_e32 v101, v2
	v_mov_b32_e32 v102, v2
	v_mov_b32_e32 v103, v2
	v_mov_b32_e32 v104, v2
	v_mov_b32_e32 v105, v2
	v_mov_b32_e32 v106, v2
	v_mov_b32_e32 v107, v2
	v_mov_b32_e32 v108, v2
	v_mov_b32_e32 v109, v2
	v_mov_b32_e32 v110, v2
	v_mov_b32_e32 v111, v2
	v_mov_b32_e32 v112, v2
	v_mov_b32_e32 v113, v2
	v_mov_b32_e32 v114, v2
	v_mov_b32_e32 v115, v2
	v_mov_b32_e32 v116, v2
	v_mov_b32_e32 v117, v2
	v_mov_b32_e32 v118, v2
	v_mov_b32_e32 v119, v2
	v_mov_b32_e32 v120, v2
	v_mov_b32_e32 v121, v2
	v_mov_b32_e32 v122, v2
	v_mov_b32_e32 v123, v2
	v_mov_b32_e32 v124, v2
	v_mov_b32_e32 v125, v2
	v_mov_b32_e32 v126, v2
	v_mov_b32_e32 v127, v2
	v_mov_b32_e32 v128, v2
	v_mov_b32_e32 v129, v2
	s_waitcnt vmcnt(0) lgkmcnt(0)
	s_barrier
	v_mov_b32_e32 v132, v169
	v_mov_b32_e32 v171, v170
	s_and_b32 s30, s27, 0x10000
	v_add_u32_e32 v250, s30, v164
	v_lshl_add_u64 v[248:249], v[134:135], 0, s[28:29]
	s_nop 0
	v_readfirstlane_b32 s30, v250
	v_lshl_add_u64 v[250:251], v[248:249], 0, s[16:17]
	s_mov_b32 m0, s30
	s_nop 0
	global_load_lds_dwordx4 v[250:251], off
	v_lshl_add_u64 v[250:251], v[248:249], 0, s[18:19]
	s_add_i32 m0, s30, 0x2000
	s_nop 0
	global_load_lds_dwordx4 v[250:251], off
	v_lshl_add_u64 v[250:251], v[248:249], 0, s[20:21]
	s_add_i32 m0, s30, 0x4000
	s_nop 0
	global_load_lds_dwordx4 v[250:251], off
	v_lshl_add_u64 v[250:251], v[248:249], 0, s[22:23]
	s_add_i32 m0, s30, 0x6000
	s_nop 0
	global_load_lds_dwordx4 v[250:251], off
	v_lshl_add_u64 v[250:251], v[136:137], 0, s[28:29]
	s_add_i32 m0, s30, 0x8000
	s_nop 0
	global_load_lds_dwordx4 v[250:251], off
	v_lshl_add_u64 v[250:251], v[138:139], 0, s[28:29]
	s_add_i32 m0, s30, 0xa000
	s_nop 0
	global_load_lds_dwordx4 v[250:251], off
	v_lshl_add_u64 v[250:251], v[140:141], 0, s[28:29]
	s_add_i32 m0, s30, 0xc000
	s_nop 0
	global_load_lds_dwordx4 v[250:251], off
	v_lshl_add_u64 v[250:251], v[142:143], 0, s[28:29]
	s_add_i32 m0, s30, 0xe000
	s_nop 0
	global_load_lds_dwordx4 v[250:251], off
	s_add_u32 s28, s28, 0x80
	s_addc_u32 s29, s29, 0
	s_add_i32 s27, s27, 0x10000
	v_add_u32_e32 v252, v132, v165
	v_add_u32_e32 v253, v171, v165
	ds_read_b128 v[224:227], v252
	ds_read_b128 v[232:235], v253 offset:32768
	ds_read_b128 v[236:239], v253 offset:36864
	ds_read_b128 v[240:243], v253 offset:40960
	ds_read_b128 v[244:247], v253 offset:45056
	ds_read_b128 v[228:231], v252 offset:4096
; #define MFMA(a, b, c) __builtin_amdgcn_mfma_f32_32x32x16_bf16((a), (b), (c), 0, 0, 0)
; #define GEMM_ISSUE(KT, ST) do { const int k1_ = (KT) << 6; unsigned char* d_ = ldst + (ST) * STAGE; \
;         _Pragma("unroll") for (int j_ = 0; j_ < 4; ++j_) dma16(ap + (size_t)(64 * j_) * lda + k1_, d_ + j_ * 8192); \
;         _Pragma("unroll") for (int j_ = 0; j_ < NBW; ++j_) dma16(bp + bro[j_] + k1_, d_ + BOFF + j_ * 8192); } while (0)
; template <int NBW>
; DI void gemm_mainloop(f32x16 (&acc)[2][NBW], const bf16_t* A, size_t lda, int m0, const bf16_t* Bt, size_t ldb, int n0, int K, unsigned char* lds, bool pre = false, bool only_issue = false) {
;     ...
; #pragma unroll 1
;     for (int kt = 0; kt < nk; ++kt) {
;         const unsigned char* st = lds + (kt & 1) * STAGE;
; #pragma unroll
;         for (int s = 0; s < 4; ++s) {
;             if (s == 1 && kt + 1 < nk) GEMM_ISSUE(kt + 1, (kt + 1) & 1);
;             bf16x8 a[2], b[NBW];
; #pragma unroll
;             for (int mb = 0; mb < 2; ++mb) a[mb] = *(const bf16x8*)(st + aofs + mb * 4096 + xo[s]);
; #pragma unroll
;             for (int nb = 0; nb < NBW; ++nb) b[nb] = *(const bf16x8*)(st + bofs + nb * 4096 + xo[s]);
; #pragma unroll
;             for (int mb = 0; mb < 2; ++mb)
; #pragma unroll
;                 for (int nb = 0; nb < NBW; ++nb) acc[mb][nb] = MFMA(a[mb], b[nb], acc[mb][nb]);
;         }
;         __syncthreads();
.Lp6_kloop:
	v_add_u32_e32 v252, v132, v166
	v_add_u32_e32 v253, v171, v166
	ds_read_b128 v[172:175], v252
	ds_read_b128 v[180:183], v253 offset:32768
	ds_read_b128 v[184:187], v253 offset:36864
	ds_read_b128 v[188:191], v253 offset:40960
	ds_read_b128 v[192:195], v253 offset:45056
	ds_read_b128 v[176:179], v252 offset:4096
	s_waitcnt lgkmcnt(6)
	v_mfma_f32_32x32x16_bf16 v[114:129], v[224:227], v[232:235], v[114:129]
	v_mfma_f32_32x32x16_bf16 v[98:113], v[224:227], v[236:239], v[98:113]
	v_mfma_f32_32x32x16_bf16 v[82:97], v[224:227], v[240:243], v[82:97]
	v_mfma_f32_32x32x16_bf16 v[66:81], v[224:227], v[244:247], v[66:81]
	v_mfma_f32_32x32x16_bf16 v[50:65], v[228:231], v[232:235], v[50:65]
	v_mfma_f32_32x32x16_bf16 v[34:49], v[228:231], v[236:239], v[34:49]
	v_mfma_f32_32x32x16_bf16 v[18:33], v[228:231], v[240:243], v[18:33]
	v_mfma_f32_32x32x16_bf16 v[2:17], v[228:231], v[244:247], v[2:17]
	v_add_u32_e32 v252, v132, v167
	v_add_u32_e32 v253, v171, v167
	ds_read_b128 v[224:227], v252
	ds_read_b128 v[232:235], v253 offset:32768
	ds_read_b128 v[236:239], v253 offset:36864
	ds_read_b128 v[240:243], v253 offset:40960
	ds_read_b128 v[244:247], v253 offset:45056
	ds_read_b128 v[228:231], v252 offset:4096
	s_waitcnt lgkmcnt(6)
	v_mfma_f32_32x32x16_bf16 v[114:129], v[172:175], v[180:183], v[114:129]
	v_mfma_f32_32x32x16_bf16 v[98:113], v[172:175], v[184:187], v[98:113]
	v_mfma_f32_32x32x16_bf16 v[82:97], v[172:175], v[188:191], v[82:97]
	v_mfma_f32_32x32x16_bf16 v[66:81], v[172:175], v[192:195], v[66:81]
	v_mfma_f32_32x32x16_bf16 v[50:65], v[176:179], v[180:183], v[50:65]
	v_mfma_f32_32x32x16_bf16 v[34:49], v[176:179], v[184:187], v[34:49]
	v_mfma_f32_32x32x16_bf16 v[18:33], v[176:179], v[188:191], v[18:33]
	v_mfma_f32_32x32x16_bf16 v[2:17], v[176:179], v[192:195], v[2:17]
	v_add_u32_e32 v252, v132, v168
	v_add_u32_e32 v253, v171, v168
	ds_read_b128 v[172:175], v252
	ds_read_b128 v[180:183], v253 offset:32768
	ds_read_b128 v[184:187], v253 offset:36864
	ds_read_b128 v[188:191], v253 offset:40960
	ds_read_b128 v[192:195], v253 offset:45056
	ds_read_b128 v[176:179], v252 offset:4096
	s_waitcnt lgkmcnt(6)
	v_mfma_f32_32x32x16_bf16 v[114:129], v[224:227], v[232:235], v[114:129]
	v_mfma_f32_32x32x16_bf16 v[98:113], v[224:227], v[236:239], v[98:113]
	v_mfma_f32_32x32x16_bf16 v[82:97], v[224:227], v[240:243], v[82:97]
	v_mfma_f32_32x32x16_bf16 v[66:81], v[224:227], v[244:247], v[66:81]
	v_mfma_f32_32x32x16_bf16 v[50:65], v[228:231], v[232:235], v[50:65]
	v_mfma_f32_32x32x16_bf16 v[34:49], v[228:231], v[236:239], v[34:49]
	v_mfma_f32_32x32x16_bf16 v[18:33], v[228:231], v[240:243], v[18:33]
	v_mfma_f32_32x32x16_bf16 v[2:17], v[228:231], v[244:247], v[2:17]
	v_xor_b32_e32 v132, 0x10000, v132
	v_xor_b32_e32 v171, 0x10000, v171
	s_waitcnt vmcnt(0) lgkmcnt(0)
	s_barrier
	s_cmp_eq_u32 s28, 0x800
	s_cbranch_scc1 .Lp6_klast
	v_add_u32_e32 v252, v132, v165
	v_add_u32_e32 v253, v171, v165
	ds_read_b128 v[224:227], v252
	ds_read_b128 v[232:235], v253 offset:32768
	ds_read_b128 v[236:239], v253 offset:36864
	ds_read_b128 v[240:243], v253 offset:40960
	ds_read_b128 v[244:247], v253 offset:45056
	ds_read_b128 v[228:231], v252 offset:4096
	s_cmp_eq_u32 s28, 0x780
	s_cbranch_scc1 .Lp6_knodma
	v_mfma_f32_32x32x16_bf16 v[114:129], v[172:175], v[180:183], v[114:129]
	s_and_b32 s30, s27, 0x10000
	v_add_u32_e32 v250, s30, v164
	v_lshl_add_u64 v[248:249], v[134:135], 0, s[28:29]
	s_nop 0
	v_readfirstlane_b32 s30, v250
	v_lshl_add_u64 v[250:251], v[248:249], 0, s[16:17]
	s_mov_b32 m0, s30
	s_nop 0
	global_load_lds_dwordx4 v[250:251], off
	v_mfma_f32_32x32x16_bf16 v[98:113], v[172:175], v[184:187], v[98:113]
	v_lshl_add_u64 v[250:251], v[248:249], 0, s[18:19]
	s_add_i32 m0, s30, 0x2000
	s_nop 0
	global_load_lds_dwordx4 v[250:251], off
	v_mfma_f32_32x32x16_bf16 v[82:97], v[172:175], v[188:191], v[82:97]
	v_lshl_add_u64 v[250:251], v[248:249], 0, s[20:21]
	s_add_i32 m0, s30, 0x4000
	s_nop 0
	global_load_lds_dwordx4 v[250:251], off
	v_mfma_f32_32x32x16_bf16 v[66:81], v[172:175], v[192:195], v[66:81]
	v_lshl_add_u64 v[250:251], v[248:249], 0, s[22:23]
	s_add_i32 m0, s30, 0x6000
	s_nop 0
	global_load_lds_dwordx4 v[250:251], off
	v_mfma_f32_32x32x16_bf16 v[50:65], v[176:179], v[180:183], v[50:65]
	v_lshl_add_u64 v[250:251], v[136:137], 0, s[28:29]
	s_add_i32 m0, s30, 0x8000
	s_nop 0
	global_load_lds_dwordx4 v[250:251], off
	v_mfma_f32_32x32x16_bf16 v[34:49], v[176:179], v[184:187], v[34:49]
	v_lshl_add_u64 v[250:251], v[138:139], 0, s[28:29]
	s_add_i32 m0, s30, 0xa000
	s_nop 0
	global_load_lds_dwordx4 v[250:251], off
	v_mfma_f32_32x32x16_bf16 v[18:33], v[176:179], v[188:191], v[18:33]
	v_lshl_add_u64 v[250:251], v[140:141], 0, s[28:29]
	s_add_i32 m0, s30, 0xc000
	s_nop 0
	global_load_lds_dwordx4 v[250:251], off
	v_mfma_f32_32x32x16_bf16 v[2:17], v[176:179], v[192:195], v[2:17]
	v_lshl_add_u64 v[250:251], v[142:143], 0, s[28:29]
	s_add_i32 m0, s30, 0xe000
	s_nop 0
	global_load_lds_dwordx4 v[250:251], off
	s_add_u32 s28, s28, 0x80
	s_addc_u32 s29, s29, 0
	s_add_i32 s27, s27, 0x10000
	s_branch .Lp6_kloop
.Lp6_knodma:
	v_mfma_f32_32x32x16_bf16 v[114:129], v[172:175], v[180:183], v[114:129]
	v_mfma_f32_32x32x16_bf16 v[98:113], v[172:175], v[184:187], v[98:113]
	v_mfma_f32_32x32x16_bf16 v[82:97], v[172:175], v[188:191], v[82:97]
	v_mfma_f32_32x32x16_bf16 v[66:81], v[172:175], v[192:195], v[66:81]
	v_mfma_f32_32x32x16_bf16 v[50:65], v[176:179], v[180:183], v[50:65]
	v_mfma_f32_32x32x16_bf16 v[34:49], v[176:179], v[184:187], v[34:49]
	v_mfma_f32_32x32x16_bf16 v[18:33], v[176:179], v[188:191], v[18:33]
	v_mfma_f32_32x32x16_bf16 v[2:17], v[176:179], v[192:195], v[2:17]
	s_add_u32 s28, s28, 0x80
	s_addc_u32 s29, s29, 0
	s_add_i32 s27, s27, 0x10000
	s_branch .Lp6_kloop
.Lp6_klast:
	v_mfma_f32_32x32x16_bf16 v[114:129], v[172:175], v[180:183], v[114:129]
	v_mfma_f32_32x32x16_bf16 v[98:113], v[172:175], v[184:187], v[98:113]
	v_mfma_f32_32x32x16_bf16 v[82:97], v[172:175], v[188:191], v[82:97]
	v_mfma_f32_32x32x16_bf16 v[66:81], v[172:175], v[192:195], v[66:81]
	v_mfma_f32_32x32x16_bf16 v[50:65], v[176:179], v[180:183], v[50:65]
	v_mfma_f32_32x32x16_bf16 v[34:49], v[176:179], v[184:187], v[34:49]
	v_mfma_f32_32x32x16_bf16 v[18:33], v[176:179], v[188:191], v[18:33]
	v_mfma_f32_32x32x16_bf16 v[2:17], v[176:179], v[192:195], v[2:17]
	s_mov_b32 s25, 16
	s_mov_b32 s30, 0x10000

; DI int opaque_tid() { int t = threadIdx.x; asm volatile("" : "+v"(t)); return t; }
; DI f32x16 zero16() { f32x16 z; for (int i = 0; i < 16; ++i) z[i] = 0.f; return z; }
; #define GEMM_ISSUE(KT, ST) do { const int k1_ = (KT) << 6; unsigned char* d_ = ldst + (ST) * STAGE; \
;         _Pragma("unroll") for (int j_ = 0; j_ < 4; ++j_) dma16(ap + (size_t)(64 * j_) * lda + k1_, d_ + j_ * 8192); \
;         _Pragma("unroll") for (int j_ = 0; j_ < NBW; ++j_) dma16(bp + bro[j_] + k1_, d_ + BOFF + j_ * 8192); } while (0)
; template <int NBW>
; DI void gemm_mainloop(f32x16 (&acc)[2][NBW], const bf16_t* A, size_t lda, int m0, const bf16_t* Bt, size_t ldb, int n0, int K, unsigned char* lds, bool pre = false, bool only_issue = false) {
;     ...
;     const int t = opaque_tid(), w = t >> 6, lane = t & 63, r = lane & 31, hh = lane >> 5, wm = w >> 1, wn = w & 1;
;     const int drow = w * 8 + (lane >> 3);
;     const int lchunk = (lane & 7) ^ ((drow >> 1) & 7);
;     const bf16_t* ap = A + (size_t)(m0 + drow) * lda + lchunk * 8;
;     const bf16_t* bp = Bt + (size_t)n0 * ldb + lchunk * 8;
;     size_t bro[NBW];
; #pragma unroll
;     for (int j = 0; j < NBW; ++j) {
;         const int rho = 64 * j + drow; const int wnh = rho / (32 * NBW), wi = rho % (32 * NBW);
;         bro[j] = (size_t)(wnh * 32 * NBW + NBW * (wi & 31) + (wi >> 5)) * ldb;
;     }
;     unsigned char* ldst = lds + w * 1024 + lane * 16;
;     ...
;     if (!pre) GEMM_ISSUE(0, 0);
;     if (only_issue) return;
;     __syncthreads();
;     const int nk = K >> 6;
;     const int xr = (r >> 1) & 7;
;     int xo[4];
; #pragma unroll
;     for (int s = 0; s < 4; ++s) xo[s] = ((2 * s + hh) ^ xr) << 4;
;     const int aofs = (wm * 64 + r) * 128;
;     const int bofs = BOFF + (wn * 32 * NBW + r) * 128;
; DI void phase_p7(const Params& P, unsigned char* lds) {
;     ...
;         f32x16 acc[2][4];
; #pragma unroll
;         for (int a = 0; a < 2; ++a)
; #pragma unroll
;             for (int b = 0; b < 4; ++b) acc[a][b] = zero16();
;         gemm_mainloop<4>(acc, U, 4096, m0, W, 4096, n0, 4096, lds, pre);
.LBB0_1721:
	v_and_b32_e32 v15, 31, v13
	v_lshlrev_b32_e32 v12, 7, v12
	s_add_i32 s48, s48, s19
	v_lshrrev_b32_e32 v17, 6, v13
	v_and_or_b32 v12, v12, s28, v15
	v_add_u32_e32 v7, s48, v7
	v_lshrrev_b32_e32 v16, 5, v14
	v_lshrrev_b32_e32 v14, 3, v14
	v_lshlrev_b32_e32 v153, 7, v12
	v_add3_u32 v12, v7, v2, s28
	v_lshlrev_b16_e32 v2, 3, v17
	v_or_b32_e32 v7, v2, v14
	v_sub_u16_e32 v2, v7, v3
	v_and_b32_e32 v2, 31, v2
	v_lshl_add_u32 v2, v2, 2, v8
	v_ashrrev_i32_e32 v3, 31, v2
	v_lshlrev_b64 v[2:3], 13, v[2:3]
	v_lshl_add_u64 v[2:3], v[2:3], 0, s[22:23]
	v_lshl_add_u64 v[2:3], v[2:3], 0, v[132:133]
	v_lshl_add_u64 v[136:137], s[2:3], 0, v[2:3]
	v_sub_u16_e32 v2, v7, v4
	v_and_b32_e32 v2, 31, v2
	v_lshl_add_u32 v2, v2, 2, v9
	v_ashrrev_i32_e32 v3, 31, v2
	v_lshlrev_b64 v[2:3], 13, v[2:3]
	v_lshl_add_u64 v[2:3], v[2:3], 0, s[22:23]
	v_lshl_add_u64 v[2:3], v[2:3], 0, v[132:133]
	v_lshl_add_u64 v[138:139], s[2:3], 0, v[2:3]
	v_sub_u16_e32 v2, v7, v5
	v_and_b32_e32 v2, 31, v2
	v_lshl_add_u32 v2, v2, 2, v10
	v_ashrrev_i32_e32 v3, 31, v2
	v_lshlrev_b64 v[2:3], 13, v[2:3]
	v_lshl_add_u64 v[2:3], v[2:3], 0, s[22:23]
	v_lshl_add_u64 v[2:3], v[2:3], 0, v[132:133]
	v_lshrrev_b32_e32 v18, 1, v13
	v_lshl_add_u64 v[140:141], s[2:3], 0, v[2:3]
	v_sub_u16_e32 v2, v7, v6
	v_bfe_u32 v13, v13, 1, 3
	v_bitop3_b32 v19, v16, v18, 7 bitop3:0x78
	v_and_b32_e32 v2, 31, v2
	v_lshlrev_b32_e32 v148, 4, v19
	v_bitop3_b32 v19, v16, v13, 2 bitop3:0x36
	v_lshl_add_u32 v2, v2, 2, v11
	v_lshlrev_b32_e32 v149, 4, v19
	v_bitop3_b32 v19, v16, v13, 4 bitop3:0x36
	v_bitop3_b32 v13, v16, v13, 6 bitop3:0x36
	v_ashrrev_i32_e32 v3, 31, v2
	v_lshlrev_b32_e32 v151, 4, v13
	v_and_or_b32 v13, v18, s34, v15
	v_lshlrev_b64 v[2:3], 13, v[2:3]
	v_lshlrev_b32_e32 v152, 7, v13
	v_ashrrev_i32_e32 v13, 31, v12
	v_lshl_add_u64 v[2:3], v[2:3], 0, s[22:23]
	v_lshlrev_b64 v[12:13], 13, v[12:13]
	v_lshl_add_u64 v[2:3], v[2:3], 0, v[132:133]
	v_or_b32_e32 v12, v12, v132
	v_lshl_add_u64 v[142:143], s[2:3], 0, v[2:3]
	v_mov_b32_e32 v2, 0
	v_lshlrev_b32_e32 v150, 4, v19
	v_lshl_add_u64 v[134:135], s[50:51], 0, v[12:13]
	s_mov_b32 s19, 0
	s_mov_b64 s[22:23], 0
	s_mov_b32 s21, 0x10000
	v_mov_b32_e32 v3, v2
	v_mov_b32_e32 v4, v2
	v_mov_b32_e32 v5, v2
	v_mov_b32_e32 v6, v2
	v_mov_b32_e32 v7, v2
	v_mov_b32_e32 v8, v2
	v_mov_b32_e32 v9, v2
	v_mov_b32_e32 v10, v2
	v_mov_b32_e32 v11, v2
	v_mov_b32_e32 v12, v2
	v_mov_b32_e32 v13, v2
	v_mov_b32_e32 v14, v2
	v_mov_b32_e32 v15, v2
	v_mov_b32_e32 v16, v2
	v_mov_b32_e32 v17, v2
	v_mov_b32_e32 v18, v2
	v_mov_b32_e32 v19, v2
	v_mov_b32_e32 v20, v2
	v_mov_b32_e32 v21, v2
	v_mov_b32_e32 v22, v2
	v_mov_b32_e32 v23, v2
	v_mov_b32_e32 v24, v2
	v_mov_b32_e32 v25, v2
	v_mov_b32_e32 v26, v2
	v_mov_b32_e32 v27, v2
	v_mov_b32_e32 v28, v2
	v_mov_b32_e32 v29, v2
	v_mov_b32_e32 v30, v2
	v_mov_b32_e32 v31, v2
	v_mov_b32_e32 v32, v2
	v_mov_b32_e32 v33, v2
	v_mov_b32_e32 v34, v2
	v_mov_b32_e32 v35, v2
	v_mov_b32_e32 v36, v2
	v_mov_b32_e32 v37, v2
	v_mov_b32_e32 v38, v2
	v_mov_b32_e32 v39, v2
	v_mov_b32_e32 v40, v2
	v_mov_b32_e32 v41, v2
	v_mov_b32_e32 v42, v2
	v_mov_b32_e32 v43, v2
	v_mov_b32_e32 v44, v2
	v_mov_b32_e32 v45, v2
	v_mov_b32_e32 v46, v2
	v_mov_b32_e32 v47, v2
	v_mov_b32_e32 v48, v2
	v_mov_b32_e32 v49, v2
	v_mov_b32_e32 v50, v2
	v_mov_b32_e32 v51, v2
	v_mov_b32_e32 v52, v2
	v_mov_b32_e32 v53, v2
	v_mov_b32_e32 v54, v2
	v_mov_b32_e32 v55, v2
	v_mov_b32_e32 v56, v2
	v_mov_b32_e32 v57, v2
	v_mov_b32_e32 v58, v2
	v_mov_b32_e32 v59, v2
	v_mov_b32_e32 v60, v2
	v_mov_b32_e32 v61, v2
	v_mov_b32_e32 v62, v2
	v_mov_b32_e32 v63, v2
	v_mov_b32_e32 v64, v2
	v_mov_b32_e32 v65, v2
	v_mov_b32_e32 v66, v2
	v_mov_b32_e32 v67, v2
	v_mov_b32_e32 v68, v2
	v_mov_b32_e32 v69, v2
	v_mov_b32_e32 v70, v2
	v_mov_b32_e32 v71, v2
	v_mov_b32_e32 v72, v2
	v_mov_b32_e32 v73, v2
	v_mov_b32_e32 v74, v2
	v_mov_b32_e32 v75, v2
	v_mov_b32_e32 v76, v2
	v_mov_b32_e32 v77, v2
	v_mov_b32_e32 v78, v2
	v_mov_b32_e32 v79, v2
	v_mov_b32_e32 v80, v2
	v_mov_b32_e32 v81, v2
	v_mov_b32_e32 v82, v2
	v_mov_b32_e32 v83, v2
	v_mov_b32_e32 v84, v2
	v_mov_b32_e32 v85, v2
	v_mov_b32_e32 v86, v2
	v_mov_b32_e32 v87, v2
	v_mov_b32_e32 v88, v2
	v_mov_b32_e32 v89, v2
	v_mov_b32_e32 v90, v2
	v_mov_b32_e32 v91, v2
	v_mov_b32_e32 v92, v2
	v_mov_b32_e32 v93, v2
	v_mov_b32_e32 v94, v2
	v_mov_b32_e32 v95, v2
	v_mov_b32_e32 v96, v2
	v_mov_b32_e32 v97, v2
	v_mov_b32_e32 v98, v2
	v_mov_b32_e32 v99, v2
	v_mov_b32_e32 v100, v2
	v_mov_b32_e32 v101, v2
	v_mov_b32_e32 v102, v2
	v_mov_b32_e32 v103, v2
	v_mov_b32_e32 v104, v2
	v_mov_b32_e32 v105, v2
	v_mov_b32_e32 v106, v2
	v_mov_b32_e32 v107, v2
	v_mov_b32_e32 v108, v2
	v_mov_b32_e32 v109, v2
	v_mov_b32_e32 v110, v2
	v_mov_b32_e32 v111, v2
	v_mov_b32_e32 v112, v2
	v_mov_b32_e32 v113, v2
	v_mov_b32_e32 v114, v2
	v_mov_b32_e32 v115, v2
	v_mov_b32_e32 v116, v2
	v_mov_b32_e32 v117, v2
	v_mov_b32_e32 v118, v2
	v_mov_b32_e32 v119, v2
	v_mov_b32_e32 v120, v2
	v_mov_b32_e32 v121, v2
	v_mov_b32_e32 v122, v2
	v_mov_b32_e32 v123, v2
	v_mov_b32_e32 v124, v2
	v_mov_b32_e32 v125, v2
	v_mov_b32_e32 v126, v2
	v_mov_b32_e32 v127, v2
	v_mov_b32_e32 v128, v2
	v_mov_b32_e32 v129, v2
	s_waitcnt vmcnt(0) lgkmcnt(0)
	s_barrier
	v_mov_b32_e32 v132, v152
	v_mov_b32_e32 v154, v153
	s_and_b32 s24, s21, 0x10000
	v_add_u32_e32 v250, s24, v147
	v_lshl_add_u64 v[248:249], v[134:135], 0, s[22:23]
	s_nop 0
	v_readfirstlane_b32 s24, v250
	v_lshl_add_u64 v[250:251], v[248:249], 0, s[10:11]
	s_mov_b32 m0, s24
	s_nop 0
	global_load_lds_dwordx4 v[250:251], off
	v_lshl_add_u64 v[250:251], v[248:249], 0, s[12:13]
	s_add_i32 m0, s24, 0x2000
	s_nop 0
	global_load_lds_dwordx4 v[250:251], off
	v_lshl_add_u64 v[250:251], v[248:249], 0, s[14:15]
	s_add_i32 m0, s24, 0x4000
	s_nop 0
	global_load_lds_dwordx4 v[250:251], off
	v_lshl_add_u64 v[250:251], v[248:249], 0, s[16:17]
	s_add_i32 m0, s24, 0x6000
	s_nop 0
	global_load_lds_dwordx4 v[250:251], off
	v_lshl_add_u64 v[250:251], v[136:137], 0, s[22:23]
	s_add_i32 m0, s24, 0x8000
	s_nop 0
	global_load_lds_dwordx4 v[250:251], off
	v_lshl_add_u64 v[250:251], v[138:139], 0, s[22:23]
	s_add_i32 m0, s24, 0xa000
	s_nop 0
	global_load_lds_dwordx4 v[250:251], off
	v_lshl_add_u64 v[250:251], v[140:141], 0, s[22:23]
	s_add_i32 m0, s24, 0xc000
	s_nop 0
	global_load_lds_dwordx4 v[250:251], off
	v_lshl_add_u64 v[250:251], v[142:143], 0, s[22:23]
	s_add_i32 m0, s24, 0xe000
	s_nop 0
	global_load_lds_dwordx4 v[250:251], off
	s_add_u32 s22, s22, 0x80
	s_addc_u32 s23, s23, 0
	s_add_i32 s21, s21, 0x10000
	v_add_u32_e32 v252, v132, v148
	v_add_u32_e32 v253, v154, v148
	ds_read_b128 v[224:227], v252
	ds_read_b128 v[232:235], v253 offset:32768
	ds_read_b128 v[236:239], v253 offset:36864
	ds_read_b128 v[240:243], v253 offset:40960
	ds_read_b128 v[244:247], v253 offset:45056
	ds_read_b128 v[228:231], v252 offset:4096
; #define MFMA(a, b, c) __builtin_amdgcn_mfma_f32_32x32x16_bf16((a), (b), (c), 0, 0, 0)
; #define GEMM_ISSUE(KT, ST) do { const int k1_ = (KT) << 6; unsigned char* d_ = ldst + (ST) * STAGE; \
;         _Pragma("unroll") for (int j_ = 0; j_ < 4; ++j_) dma16(ap + (size_t)(64 * j_) * lda + k1_, d_ + j_ * 8192); \
;         _Pragma("unroll") for (int j_ = 0; j_ < NBW; ++j_) dma16(bp + bro[j_] + k1_, d_ + BOFF + j_ * 8192); } while (0)
; template <int NBW>
; DI void gemm_mainloop(f32x16 (&acc)[2][NBW], const bf16_t* A, size_t lda, int m0, const bf16_t* Bt, size_t ldb, int n0, int K, unsigned char* lds, bool pre = false, bool only_issue = false) {
;     ...
; #pragma unroll 1
;     for (int kt = 0; kt < nk; ++kt) {
;         const unsigned char* st = lds + (kt & 1) * STAGE;
; #pragma unroll
;         for (int s = 0; s < 4; ++s) {
;             if (s == 1 && kt + 1 < nk) GEMM_ISSUE(kt + 1, (kt + 1) & 1);
;             bf16x8 a[2], b[NBW];
; #pragma unroll
;             for (int mb = 0; mb < 2; ++mb) a[mb] = *(const bf16x8*)(st + aofs + mb * 4096 + xo[s]);
; #pragma unroll
;             for (int nb = 0; nb < NBW; ++nb) b[nb] = *(const bf16x8*)(st + bofs + nb * 4096 + xo[s]);
; #pragma unroll
;             for (int mb = 0; mb < 2; ++mb)
; #pragma unroll
;                 for (int nb = 0; nb < NBW; ++nb) acc[mb][nb] = MFMA(a[mb], b[nb], acc[mb][nb]);
;         }
;         __syncthreads();
.Lp7_kloop:
	v_add_u32_e32 v252, v132, v149
	v_add_u32_e32 v253, v154, v149
	ds_read_b128 v[156:159], v252
	ds_read_b128 v[164:167], v253 offset:32768
	ds_read_b128 v[168:171], v253 offset:36864
	ds_read_b128 v[172:175], v253 offset:40960
	ds_read_b128 v[176:179], v253 offset:45056
	ds_read_b128 v[160:163], v252 offset:4096
	s_waitcnt lgkmcnt(6)
	v_mfma_f32_32x32x16_bf16 v[114:129], v[224:227], v[232:235], v[114:129]
	v_mfma_f32_32x32x16_bf16 v[98:113], v[224:227], v[236:239], v[98:113]
	v_mfma_f32_32x32x16_bf16 v[82:97], v[224:227], v[240:243], v[82:97]
	v_mfma_f32_32x32x16_bf16 v[66:81], v[224:227], v[244:247], v[66:81]
	v_mfma_f32_32x32x16_bf16 v[50:65], v[228:231], v[232:235], v[50:65]
	v_mfma_f32_32x32x16_bf16 v[34:49], v[228:231], v[236:239], v[34:49]
	v_mfma_f32_32x32x16_bf16 v[18:33], v[228:231], v[240:243], v[18:33]
	v_mfma_f32_32x32x16_bf16 v[2:17], v[228:231], v[244:247], v[2:17]
	v_add_u32_e32 v252, v132, v150
	v_add_u32_e32 v253, v154, v150
	ds_read_b128 v[224:227], v252
	ds_read_b128 v[232:235], v253 offset:32768
	ds_read_b128 v[236:239], v253 offset:36864
	ds_read_b128 v[240:243], v253 offset:40960
	ds_read_b128 v[244:247], v253 offset:45056
	ds_read_b128 v[228:231], v252 offset:4096
	s_waitcnt lgkmcnt(6)
	v_mfma_f32_32x32x16_bf16 v[114:129], v[156:159], v[164:167], v[114:129]
	v_mfma_f32_32x32x16_bf16 v[98:113], v[156:159], v[168:171], v[98:113]
	v_mfma_f32_32x32x16_bf16 v[82:97], v[156:159], v[172:175], v[82:97]
	v_mfma_f32_32x32x16_bf16 v[66:81], v[156:159], v[176:179], v[66:81]
	v_mfma_f32_32x32x16_bf16 v[50:65], v[160:163], v[164:167], v[50:65]
	v_mfma_f32_32x32x16_bf16 v[34:49], v[160:163], v[168:171], v[34:49]
	v_mfma_f32_32x32x16_bf16 v[18:33], v[160:163], v[172:175], v[18:33]
	v_mfma_f32_32x32x16_bf16 v[2:17], v[160:163], v[176:179], v[2:17]
	v_add_u32_e32 v252, v132, v151
	v_add_u32_e32 v253, v154, v151
	ds_read_b128 v[156:159], v252
	ds_read_b128 v[164:167], v253 offset:32768
	ds_read_b128 v[168:171], v253 offset:36864
	ds_read_b128 v[172:175], v253 offset:40960
	ds_read_b128 v[176:179], v253 offset:45056
	ds_read_b128 v[160:163], v252 offset:4096
	s_waitcnt lgkmcnt(6)
	v_mfma_f32_32x32x16_bf16 v[114:129], v[224:227], v[232:235], v[114:129]
	v_mfma_f32_32x32x16_bf16 v[98:113], v[224:227], v[236:239], v[98:113]
	v_mfma_f32_32x32x16_bf16 v[82:97], v[224:227], v[240:243], v[82:97]
	v_mfma_f32_32x32x16_bf16 v[66:81], v[224:227], v[244:247], v[66:81]
	v_mfma_f32_32x32x16_bf16 v[50:65], v[228:231], v[232:235], v[50:65]
	v_mfma_f32_32x32x16_bf16 v[34:49], v[228:231], v[236:239], v[34:49]
	v_mfma_f32_32x32x16_bf16 v[18:33], v[228:231], v[240:243], v[18:33]
	v_mfma_f32_32x32x16_bf16 v[2:17], v[228:231], v[244:247], v[2:17]
	v_xor_b32_e32 v132, 0x10000, v132
	v_xor_b32_e32 v154, 0x10000, v154
	s_waitcnt vmcnt(0) lgkmcnt(0)
	s_barrier
	s_cmp_eq_u32 s22, 0x2000
	s_cbranch_scc1 .Lp7_klast
	v_add_u32_e32 v252, v132, v148
	v_add_u32_e32 v253, v154, v148
	ds_read_b128 v[224:227], v252
	ds_read_b128 v[232:235], v253 offset:32768
	ds_read_b128 v[236:239], v253 offset:36864
	ds_read_b128 v[240:243], v253 offset:40960
	ds_read_b128 v[244:247], v253 offset:45056
	ds_read_b128 v[228:231], v252 offset:4096
	s_cmp_eq_u32 s22, 0x1f80
	s_cbranch_scc1 .Lp7_knodma
	v_mfma_f32_32x32x16_bf16 v[114:129], v[156:159], v[164:167], v[114:129]
	s_and_b32 s24, s21, 0x10000
	v_add_u32_e32 v250, s24, v147
	v_lshl_add_u64 v[248:249], v[134:135], 0, s[22:23]
	s_nop 0
	v_readfirstlane_b32 s24, v250
	v_lshl_add_u64 v[250:251], v[248:249], 0, s[10:11]
	s_mov_b32 m0, s24
	s_nop 0
	global_load_lds_dwordx4 v[250:251], off
	v_mfma_f32_32x32x16_bf16 v[98:113], v[156:159], v[168:171], v[98:113]
	v_lshl_add_u64 v[250:251], v[248:249], 0, s[12:13]
	s_add_i32 m0, s24, 0x2000
	s_nop 0
	global_load_lds_dwordx4 v[250:251], off
	v_mfma_f32_32x32x16_bf16 v[82:97], v[156:159], v[172:175], v[82:97]
	v_lshl_add_u64 v[250:251], v[248:249], 0, s[14:15]
	s_add_i32 m0, s24, 0x4000
	s_nop 0
	global_load_lds_dwordx4 v[250:251], off
	v_mfma_f32_32x32x16_bf16 v[66:81], v[156:159], v[176:179], v[66:81]
	v_lshl_add_u64 v[250:251], v[248:249], 0, s[16:17]
	s_add_i32 m0, s24, 0x6000
	s_nop 0
	global_load_lds_dwordx4 v[250:251], off
	v_mfma_f32_32x32x16_bf16 v[50:65], v[160:163], v[164:167], v[50:65]
	v_lshl_add_u64 v[250:251], v[136:137], 0, s[22:23]
	s_add_i32 m0, s24, 0x8000
	s_nop 0
	global_load_lds_dwordx4 v[250:251], off
	v_mfma_f32_32x32x16_bf16 v[34:49], v[160:163], v[168:171], v[34:49]
	v_lshl_add_u64 v[250:251], v[138:139], 0, s[22:23]
	s_add_i32 m0, s24, 0xa000
	s_nop 0
	global_load_lds_dwordx4 v[250:251], off
	v_mfma_f32_32x32x16_bf16 v[18:33], v[160:163], v[172:175], v[18:33]
	v_lshl_add_u64 v[250:251], v[140:141], 0, s[22:23]
	s_add_i32 m0, s24, 0xc000
	s_nop 0
	global_load_lds_dwordx4 v[250:251], off
	v_mfma_f32_32x32x16_bf16 v[2:17], v[160:163], v[176:179], v[2:17]
	v_lshl_add_u64 v[250:251], v[142:143], 0, s[22:23]
	s_add_i32 m0, s24, 0xe000
	s_nop 0
	global_load_lds_dwordx4 v[250:251], off
	s_add_u32 s22, s22, 0x80
	s_addc_u32 s23, s23, 0
	s_add_i32 s21, s21, 0x10000
	s_branch .Lp7_kloop
.Lp7_knodma:
	v_mfma_f32_32x32x16_bf16 v[114:129], v[156:159], v[164:167], v[114:129]
	v_mfma_f32_32x32x16_bf16 v[98:113], v[156:159], v[168:171], v[98:113]
	v_mfma_f32_32x32x16_bf16 v[82:97], v[156:159], v[172:175], v[82:97]
	v_mfma_f32_32x32x16_bf16 v[66:81], v[156:159], v[176:179], v[66:81]
	v_mfma_f32_32x32x16_bf16 v[50:65], v[160:163], v[164:167], v[50:65]
	v_mfma_f32_32x32x16_bf16 v[34:49], v[160:163], v[168:171], v[34:49]
	v_mfma_f32_32x32x16_bf16 v[18:33], v[160:163], v[172:175], v[18:33]
	v_mfma_f32_32x32x16_bf16 v[2:17], v[160:163], v[176:179], v[2:17]
	s_add_u32 s22, s22, 0x80
	s_addc_u32 s23, s23, 0
	s_add_i32 s21, s21, 0x10000
	s_branch .Lp7_kloop
.Lp7_klast:
	v_mfma_f32_32x32x16_bf16 v[114:129], v[156:159], v[164:167], v[114:129]
	v_mfma_f32_32x32x16_bf16 v[98:113], v[156:159], v[168:171], v[98:113]
	v_mfma_f32_32x32x16_bf16 v[82:97], v[156:159], v[172:175], v[82:97]
	v_mfma_f32_32x32x16_bf16 v[66:81], v[156:159], v[176:179], v[66:81]
	v_mfma_f32_32x32x16_bf16 v[50:65], v[160:163], v[164:167], v[50:65]
	v_mfma_f32_32x32x16_bf16 v[34:49], v[160:163], v[168:171], v[34:49]
	v_mfma_f32_32x32x16_bf16 v[18:33], v[160:163], v[172:175], v[18:33]
	v_mfma_f32_32x32x16_bf16 v[2:17], v[160:163], v[176:179], v[2:17]
	s_mov_b32 s19, 64
	s_mov_b32 s24, 0x10000
